# ladder with one counted wait per 4 MFMAs + A-read reorder + no per-block setprio
# speedup vs baseline: 1.0101x; 1.0101x over previous
.LBB0_134:
	s_add_u32 s28, s66, 0xfffc0080
	s_addc_u32 s29, s67, -1
	s_add_i32 s88, 0, 0x10000
	v_add_u32_e32 v152, s88, v191
	ds_read_b128 v[128:131], v152
	ds_read_b128 v[132:135], v152 offset:1024
	ds_read_b128 v[148:151], v152 offset:2048
	ds_read_b128 v[152:155], v152 offset:3072
	s_cmp_eq_u32 vcc_lo, 12
	s_cselect_b32 s71, s5, s29
	s_cselect_b32 s70, s7, s28
	s_cselect_b32 s69, s17, s91
	s_cselect_b32 s68, s19, s85
	v_lshl_add_u64 v[172:173], s[66:67], 0, v[144:145]
	s_add_i32 m0, s73, 0xc000
	ds_read_b128 v[156:159], v192
	ds_read_b128 v[164:167], v192 offset:2048
	ds_read_b128 v[194:197], v192 offset:4096
	ds_read_b128 v[202:205], v192 offset:6144
	ds_read_b128 v[160:163], v192 offset:1024
	ds_read_b128 v[168:171], v192 offset:3072
	ds_read_b128 v[198:201], v192 offset:5120
	ds_read_b128 v[206:209], v192 offset:7168
	global_load_lds_dwordx4 v[172:173], off
	v_lshl_add_u64 v[172:173], s[66:67], 0, v[146:147]
	s_add_i32 m0, s73, 0xe000
	s_nop 0
	global_load_lds_dwordx4 v[172:173], off
	s_waitcnt lgkmcnt(8)
	s_barrier
	s_waitcnt lgkmcnt(6)
	v_mfma_f32_16x16x32_bf16 v[124:127], v[128:131], v[156:159], v[124:127]
	v_mfma_f32_16x16x32_bf16 v[120:123], v[148:151], v[156:159], v[120:123]
	v_mfma_f32_16x16x32_bf16 v[108:111], v[128:131], v[164:167], v[108:111]
	v_mfma_f32_16x16x32_bf16 v[104:107], v[148:151], v[164:167], v[104:107]
	s_waitcnt lgkmcnt(4)
	v_mfma_f32_16x16x32_bf16 v[92:95], v[128:131], v[194:197], v[92:95]
	v_mfma_f32_16x16x32_bf16 v[88:91], v[148:151], v[194:197], v[88:91]
	v_mfma_f32_16x16x32_bf16 v[76:79], v[128:131], v[202:205], v[76:79]
	v_mfma_f32_16x16x32_bf16 v[72:75], v[148:151], v[202:205], v[72:75]
	s_waitcnt lgkmcnt(2)
	v_mfma_f32_16x16x32_bf16 v[124:127], v[132:135], v[160:163], v[124:127]
	v_mfma_f32_16x16x32_bf16 v[120:123], v[152:155], v[160:163], v[120:123]
	v_mfma_f32_16x16x32_bf16 v[108:111], v[132:135], v[168:171], v[108:111]
	v_mfma_f32_16x16x32_bf16 v[104:107], v[152:155], v[168:171], v[104:107]
	s_waitcnt lgkmcnt(0)
	v_mfma_f32_16x16x32_bf16 v[92:95], v[132:135], v[198:201], v[92:95]
	v_mfma_f32_16x16x32_bf16 v[88:91], v[152:155], v[198:201], v[88:91]
	v_mfma_f32_16x16x32_bf16 v[76:79], v[132:135], v[206:209], v[76:79]
	v_mfma_f32_16x16x32_bf16 v[72:75], v[152:155], v[206:209], v[72:75]
	s_barrier
	s_add_i32 s89, 0, 0x14000
	v_add_u32_e32 v172, s89, v191
	s_add_i32 s28, s88, s72
	ds_read_b128 v[210:213], v172
	ds_read_b128 v[214:217], v172 offset:1024
	ds_read_b128 v[232:235], v172 offset:2048
	ds_read_b128 v[236:239], v172 offset:3072
	v_lshl_add_u64 v[172:173], s[68:69], 0, v[138:139]
	s_mov_b32 m0, s28
	v_lshl_add_u64 v[188:189], s[68:69], 0, v[142:143]
	global_load_lds_dwordx4 v[172:173], off
	s_add_i32 m0, s28, 0x2000
	s_nop 0
	global_load_lds_dwordx4 v[188:189], off
	s_barrier
	s_waitcnt lgkmcnt(1)
	v_mfma_f32_16x16x32_bf16 v[116:119], v[210:213], v[156:159], v[116:119]
	v_mfma_f32_16x16x32_bf16 v[112:115], v[232:235], v[156:159], v[112:115]
	v_mfma_f32_16x16x32_bf16 v[100:103], v[210:213], v[164:167], v[100:103]
	v_mfma_f32_16x16x32_bf16 v[96:99], v[232:235], v[164:167], v[96:99]
	v_mfma_f32_16x16x32_bf16 v[84:87], v[210:213], v[194:197], v[84:87]
	v_mfma_f32_16x16x32_bf16 v[80:83], v[232:235], v[194:197], v[80:83]
	v_mfma_f32_16x16x32_bf16 v[68:71], v[210:213], v[202:205], v[68:71]
	v_mfma_f32_16x16x32_bf16 v[64:67], v[232:235], v[202:205], v[64:67]
	s_waitcnt lgkmcnt(0)
	v_mfma_f32_16x16x32_bf16 v[116:119], v[214:217], v[160:163], v[116:119]
	v_mfma_f32_16x16x32_bf16 v[112:115], v[236:239], v[160:163], v[112:115]
	v_mfma_f32_16x16x32_bf16 v[100:103], v[214:217], v[168:171], v[100:103]
	v_mfma_f32_16x16x32_bf16 v[96:99], v[236:239], v[168:171], v[96:99]
	v_mfma_f32_16x16x32_bf16 v[84:87], v[214:217], v[198:201], v[84:87]
	v_mfma_f32_16x16x32_bf16 v[80:83], v[236:239], v[198:201], v[80:83]
	v_mfma_f32_16x16x32_bf16 v[68:71], v[214:217], v[206:209], v[68:71]
	v_mfma_f32_16x16x32_bf16 v[64:67], v[236:239], v[206:209], v[64:67]
	s_mov_b32 m0, s73
	v_lshl_add_u64 v[240:241], s[70:71], 0, v[136:137]
	s_barrier
	ds_read_b128 v[156:159], v192 offset:16384
	ds_read_b128 v[164:167], v192 offset:18432
	ds_read_b128 v[194:197], v192 offset:20480
	ds_read_b128 v[202:205], v192 offset:22528
	ds_read_b128 v[160:163], v192 offset:17408
	ds_read_b128 v[168:171], v192 offset:19456
	ds_read_b128 v[198:201], v192 offset:21504
	ds_read_b128 v[206:209], v192 offset:23552
	global_load_lds_dwordx4 v[240:241], off
	v_lshl_add_u64 v[242:243], s[70:71], 0, v[140:141]
	s_mov_b32 m0, s74
	s_nop 0
	global_load_lds_dwordx4 v[242:243], off
	s_barrier
	s_waitcnt lgkmcnt(6)
	v_mfma_f32_16x16x32_bf16 v[60:63], v[128:131], v[156:159], v[60:63]
	v_mfma_f32_16x16x32_bf16 v[56:59], v[148:151], v[156:159], v[56:59]
	v_mfma_f32_16x16x32_bf16 v[44:47], v[128:131], v[164:167], v[44:47]
	v_mfma_f32_16x16x32_bf16 v[40:43], v[148:151], v[164:167], v[40:43]
	s_waitcnt lgkmcnt(4)
	v_mfma_f32_16x16x32_bf16 v[28:31], v[128:131], v[194:197], v[28:31]
	v_mfma_f32_16x16x32_bf16 v[24:27], v[148:151], v[194:197], v[24:27]
	v_mfma_f32_16x16x32_bf16 v[12:15], v[128:131], v[202:205], v[12:15]
	v_mfma_f32_16x16x32_bf16 v[8:11], v[148:151], v[202:205], v[8:11]
	s_waitcnt lgkmcnt(2)
	v_mfma_f32_16x16x32_bf16 v[60:63], v[132:135], v[160:163], v[60:63]
	v_mfma_f32_16x16x32_bf16 v[56:59], v[152:155], v[160:163], v[56:59]
	v_mfma_f32_16x16x32_bf16 v[44:47], v[132:135], v[168:171], v[44:47]
	v_mfma_f32_16x16x32_bf16 v[40:43], v[152:155], v[168:171], v[40:43]
	s_waitcnt lgkmcnt(0)
	v_mfma_f32_16x16x32_bf16 v[28:31], v[132:135], v[198:201], v[28:31]
	v_mfma_f32_16x16x32_bf16 v[24:27], v[152:155], v[198:201], v[24:27]
	v_mfma_f32_16x16x32_bf16 v[12:15], v[132:135], v[206:209], v[12:15]
	v_mfma_f32_16x16x32_bf16 v[8:11], v[152:155], v[206:209], v[8:11]
	s_barrier
	s_add_u32 s28, s68, 0x40000
	s_addc_u32 s29, s69, 0
	s_add_i32 s88, s89, s72
	v_lshl_add_u64 v[128:129], s[28:29], 0, v[138:139]
	s_mov_b32 m0, s88
	s_nop 0
	global_load_lds_dwordx4 v[128:129], off
	v_lshl_add_u64 v[128:129], s[28:29], 0, v[142:143]
	s_add_i32 m0, s88, 0x2000
	s_nop 0
	global_load_lds_dwordx4 v[128:129], off
	s_waitcnt vmcnt(6)
	s_barrier
	v_mfma_f32_16x16x32_bf16 v[52:55], v[210:213], v[156:159], v[52:55]
	v_mfma_f32_16x16x32_bf16 v[48:51], v[232:235], v[156:159], v[48:51]
	v_mfma_f32_16x16x32_bf16 v[36:39], v[210:213], v[164:167], v[36:39]
	v_mfma_f32_16x16x32_bf16 v[32:35], v[232:235], v[164:167], v[32:35]
	v_mfma_f32_16x16x32_bf16 v[20:23], v[210:213], v[194:197], v[20:23]
	v_mfma_f32_16x16x32_bf16 v[16:19], v[232:235], v[194:197], v[16:19]
	v_mfma_f32_16x16x32_bf16 v[4:7], v[210:213], v[202:205], v[4:7]
	v_mfma_f32_16x16x32_bf16 v[0:3], v[232:235], v[202:205], v[0:3]
	v_mfma_f32_16x16x32_bf16 v[52:55], v[214:217], v[160:163], v[52:55]
	v_mfma_f32_16x16x32_bf16 v[48:51], v[236:239], v[160:163], v[48:51]
	v_mfma_f32_16x16x32_bf16 v[36:39], v[214:217], v[168:171], v[36:39]
	v_mfma_f32_16x16x32_bf16 v[32:35], v[236:239], v[168:171], v[32:35]
	v_mfma_f32_16x16x32_bf16 v[20:23], v[214:217], v[198:201], v[20:23]
	v_mfma_f32_16x16x32_bf16 v[16:19], v[236:239], v[198:201], v[16:19]
	v_mfma_f32_16x16x32_bf16 v[4:7], v[214:217], v[206:209], v[4:7]
	v_mfma_f32_16x16x32_bf16 v[0:3], v[236:239], v[206:209], v[0:3]
	s_add_i32 s88, 0, 0x18000
	v_add_u32_e32 v152, s88, v191
	s_barrier
	ds_read_b128 v[128:131], v152
	ds_read_b128 v[132:135], v152 offset:1024
	ds_read_b128 v[148:151], v152 offset:2048
	ds_read_b128 v[152:155], v152 offset:3072
	s_add_u32 s28, s70, 0x40000
	s_addc_u32 s29, s71, 0
	s_mov_b32 m0, s75
	v_lshl_add_u64 v[210:211], s[28:29], 0, v[136:137]
	ds_read_b128 v[156:159], v192 offset:32768
	ds_read_b128 v[164:167], v192 offset:34816
	ds_read_b128 v[194:197], v192 offset:36864
	ds_read_b128 v[202:205], v192 offset:38912
	ds_read_b128 v[160:163], v192 offset:33792
	ds_read_b128 v[168:171], v192 offset:35840
	ds_read_b128 v[198:201], v192 offset:37888
	ds_read_b128 v[206:209], v192 offset:39936
	global_load_lds_dwordx4 v[210:211], off
	v_lshl_add_u64 v[210:211], s[28:29], 0, v[140:141]
	s_mov_b32 m0, s76
	s_nop 0
	global_load_lds_dwordx4 v[210:211], off
	s_waitcnt lgkmcnt(8)
	s_barrier
	s_waitcnt lgkmcnt(6)
	v_mfma_f32_16x16x32_bf16 v[124:127], v[128:131], v[156:159], v[124:127]
	v_mfma_f32_16x16x32_bf16 v[120:123], v[148:151], v[156:159], v[120:123]
	v_mfma_f32_16x16x32_bf16 v[108:111], v[128:131], v[164:167], v[108:111]
	v_mfma_f32_16x16x32_bf16 v[104:107], v[148:151], v[164:167], v[104:107]
	s_waitcnt lgkmcnt(4)
	v_mfma_f32_16x16x32_bf16 v[92:95], v[128:131], v[194:197], v[92:95]
	v_mfma_f32_16x16x32_bf16 v[88:91], v[148:151], v[194:197], v[88:91]
	v_mfma_f32_16x16x32_bf16 v[76:79], v[128:131], v[202:205], v[76:79]
	v_mfma_f32_16x16x32_bf16 v[72:75], v[148:151], v[202:205], v[72:75]
	s_waitcnt lgkmcnt(2)
	v_mfma_f32_16x16x32_bf16 v[124:127], v[132:135], v[160:163], v[124:127]
	v_mfma_f32_16x16x32_bf16 v[120:123], v[152:155], v[160:163], v[120:123]
	v_mfma_f32_16x16x32_bf16 v[108:111], v[132:135], v[168:171], v[108:111]
	v_mfma_f32_16x16x32_bf16 v[104:107], v[152:155], v[168:171], v[104:107]
	s_waitcnt lgkmcnt(0)
	v_mfma_f32_16x16x32_bf16 v[92:95], v[132:135], v[198:201], v[92:95]
	v_mfma_f32_16x16x32_bf16 v[88:91], v[152:155], v[198:201], v[88:91]
	v_mfma_f32_16x16x32_bf16 v[76:79], v[132:135], v[206:209], v[76:79]
	v_mfma_f32_16x16x32_bf16 v[72:75], v[152:155], v[206:209], v[72:75]
	s_barrier
	s_add_i32 s70, 0, 0x1c000
	s_add_i32 s28, s88, s72
	v_add_u32_e32 v174, s70, v191
	v_lshl_add_u64 v[172:173], v[172:173], 0, s[40:41]
	s_mov_b32 m0, s28
	ds_read_b128 v[210:213], v174
	ds_read_b128 v[214:217], v174 offset:1024
	ds_read_b128 v[232:235], v174 offset:2048
	ds_read_b128 v[236:239], v174 offset:3072
	global_load_lds_dwordx4 v[172:173], off
	v_lshl_add_u64 v[172:173], v[188:189], 0, s[40:41]
	s_add_i32 m0, s28, 0x2000
	s_nop 0
	global_load_lds_dwordx4 v[172:173], off
	s_barrier
	s_waitcnt lgkmcnt(1)
	v_mfma_f32_16x16x32_bf16 v[116:119], v[210:213], v[156:159], v[116:119]
	v_mfma_f32_16x16x32_bf16 v[112:115], v[232:235], v[156:159], v[112:115]
	v_mfma_f32_16x16x32_bf16 v[100:103], v[210:213], v[164:167], v[100:103]
	v_mfma_f32_16x16x32_bf16 v[96:99], v[232:235], v[164:167], v[96:99]
	v_mfma_f32_16x16x32_bf16 v[84:87], v[210:213], v[194:197], v[84:87]
	v_mfma_f32_16x16x32_bf16 v[80:83], v[232:235], v[194:197], v[80:83]
	v_mfma_f32_16x16x32_bf16 v[68:71], v[210:213], v[202:205], v[68:71]
	v_mfma_f32_16x16x32_bf16 v[64:67], v[232:235], v[202:205], v[64:67]
	s_waitcnt lgkmcnt(0)
	v_mfma_f32_16x16x32_bf16 v[116:119], v[214:217], v[160:163], v[116:119]
	v_mfma_f32_16x16x32_bf16 v[112:115], v[236:239], v[160:163], v[112:115]
	v_mfma_f32_16x16x32_bf16 v[100:103], v[214:217], v[168:171], v[100:103]
	v_mfma_f32_16x16x32_bf16 v[96:99], v[236:239], v[168:171], v[96:99]
	v_mfma_f32_16x16x32_bf16 v[84:87], v[214:217], v[198:201], v[84:87]
	v_mfma_f32_16x16x32_bf16 v[80:83], v[236:239], v[198:201], v[80:83]
	v_mfma_f32_16x16x32_bf16 v[68:71], v[214:217], v[206:209], v[68:71]
	v_mfma_f32_16x16x32_bf16 v[64:67], v[236:239], v[206:209], v[64:67]
	s_mov_b32 m0, s79
	v_lshl_add_u64 v[172:173], v[240:241], 0, s[40:41]
	s_barrier
	ds_read_b128 v[156:159], v192 offset:49152
	ds_read_b128 v[164:167], v192 offset:51200
	ds_read_b128 v[194:197], v192 offset:53248
	ds_read_b128 v[202:205], v192 offset:55296
	ds_read_b128 v[160:163], v192 offset:50176
	ds_read_b128 v[168:171], v192 offset:52224
	ds_read_b128 v[198:201], v192 offset:54272
	ds_read_b128 v[206:209], v192 offset:56320
	global_load_lds_dwordx4 v[172:173], off
	v_lshl_add_u64 v[172:173], v[242:243], 0, s[40:41]
	s_mov_b32 m0, s80
	s_nop 0
	global_load_lds_dwordx4 v[172:173], off
	s_barrier
	s_waitcnt lgkmcnt(6)
	v_mfma_f32_16x16x32_bf16 v[60:63], v[128:131], v[156:159], v[60:63]
	v_mfma_f32_16x16x32_bf16 v[56:59], v[148:151], v[156:159], v[56:59]
	v_mfma_f32_16x16x32_bf16 v[44:47], v[128:131], v[164:167], v[44:47]
	v_mfma_f32_16x16x32_bf16 v[40:43], v[148:151], v[164:167], v[40:43]
	s_waitcnt lgkmcnt(4)
	v_mfma_f32_16x16x32_bf16 v[28:31], v[128:131], v[194:197], v[28:31]
	v_mfma_f32_16x16x32_bf16 v[24:27], v[148:151], v[194:197], v[24:27]
	v_mfma_f32_16x16x32_bf16 v[12:15], v[128:131], v[202:205], v[12:15]
	v_mfma_f32_16x16x32_bf16 v[8:11], v[148:151], v[202:205], v[8:11]
	s_waitcnt lgkmcnt(2)
	v_mfma_f32_16x16x32_bf16 v[60:63], v[132:135], v[160:163], v[60:63]
	v_mfma_f32_16x16x32_bf16 v[56:59], v[152:155], v[160:163], v[56:59]
	v_mfma_f32_16x16x32_bf16 v[44:47], v[132:135], v[168:171], v[44:47]
	v_mfma_f32_16x16x32_bf16 v[40:43], v[152:155], v[168:171], v[40:43]
	s_waitcnt lgkmcnt(0)
	v_mfma_f32_16x16x32_bf16 v[28:31], v[132:135], v[198:201], v[28:31]
	v_mfma_f32_16x16x32_bf16 v[24:27], v[152:155], v[198:201], v[24:27]
	v_mfma_f32_16x16x32_bf16 v[12:15], v[132:135], v[206:209], v[12:15]
	v_mfma_f32_16x16x32_bf16 v[8:11], v[152:155], v[206:209], v[8:11]
	s_barrier
	s_add_u32 s28, s68, 0x40080
	s_addc_u32 s29, s69, 0
	s_add_i32 s68, s70, s72
	v_lshl_add_u64 v[128:129], s[28:29], 0, v[138:139]
	s_mov_b32 m0, s68
	s_nop 0
	global_load_lds_dwordx4 v[128:129], off
	v_lshl_add_u64 v[128:129], s[28:29], 0, v[142:143]
	s_add_i32 m0, s68, 0x2000
	s_nop 0
	global_load_lds_dwordx4 v[128:129], off
	s_waitcnt vmcnt(6)
	s_barrier
	v_mfma_f32_16x16x32_bf16 v[52:55], v[210:213], v[156:159], v[52:55]
	v_mfma_f32_16x16x32_bf16 v[48:51], v[232:235], v[156:159], v[48:51]
	v_mfma_f32_16x16x32_bf16 v[36:39], v[210:213], v[164:167], v[36:39]
	v_mfma_f32_16x16x32_bf16 v[32:35], v[232:235], v[164:167], v[32:35]
	v_mfma_f32_16x16x32_bf16 v[20:23], v[210:213], v[194:197], v[20:23]
	v_mfma_f32_16x16x32_bf16 v[16:19], v[232:235], v[194:197], v[16:19]
	v_mfma_f32_16x16x32_bf16 v[4:7], v[210:213], v[202:205], v[4:7]
	v_mfma_f32_16x16x32_bf16 v[0:3], v[232:235], v[202:205], v[0:3]
	v_mfma_f32_16x16x32_bf16 v[52:55], v[214:217], v[160:163], v[52:55]
	v_mfma_f32_16x16x32_bf16 v[48:51], v[236:239], v[160:163], v[48:51]
	v_mfma_f32_16x16x32_bf16 v[36:39], v[214:217], v[168:171], v[36:39]
	v_mfma_f32_16x16x32_bf16 v[32:35], v[236:239], v[168:171], v[32:35]
	v_mfma_f32_16x16x32_bf16 v[20:23], v[214:217], v[198:201], v[20:23]
	v_mfma_f32_16x16x32_bf16 v[16:19], v[236:239], v[198:201], v[16:19]
	v_mfma_f32_16x16x32_bf16 v[4:7], v[214:217], v[206:209], v[4:7]
	v_mfma_f32_16x16x32_bf16 v[0:3], v[236:239], v[206:209], v[0:3]
	s_add_i32 vcc_lo, vcc_lo, 2
	s_add_u32 s66, s66, 0x100
	s_addc_u32 s67, s67, 0
	s_add_u32 s85, s85, 0x100
	s_addc_u32 s91, s91, 0
	s_cmp_lt_u32 vcc_lo, 14
	s_barrier
	s_cbranch_scc1 .LBB0_134
	s_lshl_b32 s4, s4, 8
	v_mov_b32_e32 v176, v175
	v_mov_b32_e32 v188, v190
	s_add_i32 s4, s4, s77
	s_cmp_gt_i32 s6, 7
	v_add_u32_e32 v148, s4, v176
	v_lshlrev_b32_e32 v128, 2, v188
	v_ashrrev_i32_e32 v129, 31, v128
	v_ashrrev_i32_e32 v149, 31, v148
	v_lshl_add_u64 v[128:129], v[128:129], 2, s[8:9]
	v_lshlrev_b64 v[130:131], 6, v[148:149]
	v_add_u32_e32 v166, 16, v148
	v_lshl_add_u64 v[130:131], v[128:129], 0, v[130:131]
	v_ashrrev_i32_e32 v167, 31, v166
	global_load_dwordx4 v[160:163], v[130:131], off
	v_lshlrev_b64 v[130:131], 6, v[166:167]
	v_lshl_add_u64 v[130:131], v[128:129], 0, v[130:131]
	global_load_dwordx4 v[168:171], v[130:131], off
	v_add_u32_e32 v164, 32, v148
	v_ashrrev_i32_e32 v165, 31, v164
	v_lshlrev_b64 v[130:131], 6, v[164:165]
	v_add_u32_e32 v158, 48, v148
	v_lshl_add_u64 v[130:131], v[128:129], 0, v[130:131]
	v_ashrrev_i32_e32 v159, 31, v158
	global_load_dwordx4 v[194:197], v[130:131], off
	v_lshlrev_b64 v[130:131], 6, v[158:159]
	v_lshl_add_u64 v[130:131], v[128:129], 0, v[130:131]
	global_load_dwordx4 v[198:201], v[130:131], off
	v_add_u32_e32 v156, 0x80, v148
	v_ashrrev_i32_e32 v157, 31, v156
	v_lshlrev_b64 v[130:131], 6, v[156:157]
	v_add_u32_e32 v154, 0x90, v148
	v_lshl_add_u64 v[130:131], v[128:129], 0, v[130:131]
	v_ashrrev_i32_e32 v155, 31, v154
	global_load_dwordx4 v[202:205], v[130:131], off
	v_lshlrev_b64 v[130:131], 6, v[154:155]
	v_add_u32_e32 v152, 0xa0, v148
	v_lshl_add_u64 v[130:131], v[128:129], 0, v[130:131]
	v_ashrrev_i32_e32 v153, 31, v152
	global_load_dwordx4 v[206:209], v[130:131], off
	v_lshlrev_b64 v[130:131], 6, v[152:153]
	v_add_u32_e32 v150, 0xb0, v148
	v_lshl_add_u64 v[130:131], v[128:129], 0, v[130:131]
	v_ashrrev_i32_e32 v151, 31, v150
	global_load_dwordx4 v[132:135], v[130:131], off
	v_lshlrev_b64 v[130:131], 6, v[150:151]
	v_lshl_add_u64 v[128:129], v[128:129], 0, v[130:131]
	global_load_dwordx4 v[128:131], v[128:129], off
	s_cselect_b64 s[66:67], -1, 0
	s_lshl_b32 s7, s6, 8
	s_add_i32 s7, s81, s7
	s_cmp_lt_i32 s6, 8
	s_mov_b64 s[68:69], -1
	s_waitcnt vmcnt(0)
	v_mov_b32_e32 v172, v161
	v_mov_b32_e32 v173, v162
	v_mov_b32_e32 v161, v163
	v_mov_b32_e32 v162, v169
	v_mov_b32_e32 v163, v170
	v_mov_b32_e32 v169, v171
	v_pk_add_f32 v[160:161], v[172:173], v[160:161]
	v_pk_add_f32 v[162:163], v[162:163], v[168:169]
	v_mov_b32_e32 v169, v160
	v_mov_b32_e32 v168, v162
	v_mov_b32_e32 v160, v163
	v_pk_add_f32 v[160:161], v[168:169], v[160:161]
	ds_bpermute_b32 v163, v219, v161
	ds_bpermute_b32 v162, v219, v160
	s_waitcnt lgkmcnt(0)
	v_pk_add_f32 v[160:161], v[160:161], v[162:163]
	ds_bpermute_b32 v163, v218, v161
	ds_bpermute_b32 v162, v218, v160
	s_waitcnt lgkmcnt(0)
	v_pk_add_f32 v[160:161], v[160:161], v[162:163]
	s_nop 0
	v_pk_fma_f32 v[172:173], v[160:161], s[30:31], v[178:179] op_sel_hi:[1,0,0]
	v_mov_b32_e32 v162, v199
	v_mul_f32_e32 v160, 0x4b800000, v173
	v_cmp_gt_f32_e32 vcc, s86, v173
	v_mov_b32_e32 v163, v200
	v_mov_b32_e32 v199, v201
	v_cndmask_b32_e32 v160, v173, v160, vcc
	v_rsq_f32_e32 v160, v160
	v_pk_add_f32 v[162:163], v[162:163], v[198:199]
	v_cmp_gt_f32_e64 s[4:5], s86, v172
	v_mov_b32_e32 v168, v162
	v_mul_f32_e32 v161, 0x45800000, v160
	v_cndmask_b32_e32 v174, v160, v161, vcc
	v_mov_b32_e32 v160, v195
	v_mov_b32_e32 v161, v196
	v_mov_b32_e32 v195, v197
	v_pk_add_f32 v[160:161], v[160:161], v[194:195]
	s_nop 0
	v_mov_b32_e32 v169, v160
	v_mov_b32_e32 v160, v163
	v_pk_add_f32 v[160:161], v[168:169], v[160:161]
	ds_bpermute_b32 v163, v219, v161
	ds_bpermute_b32 v162, v219, v160
	s_waitcnt lgkmcnt(0)
	v_pk_add_f32 v[168:169], v[160:161], v[162:163]
	v_mov_b32_e32 v160, v203
	v_mov_b32_e32 v161, v204
	v_mov_b32_e32 v203, v205
	v_mov_b32_e32 v162, v207
	v_mov_b32_e32 v163, v208
	v_mov_b32_e32 v207, v209
	v_pk_add_f32 v[160:161], v[160:161], v[202:203]
	v_pk_add_f32 v[162:163], v[162:163], v[206:207]
	v_mov_b32_e32 v195, v160
	v_mov_b32_e32 v194, v162
	v_mov_b32_e32 v160, v163
	v_pk_add_f32 v[160:161], v[194:195], v[160:161]
	v_mov_b32_e32 v194, v133
	v_mov_b32_e32 v195, v134
	v_mov_b32_e32 v133, v135
	v_mov_b32_e32 v134, v129
	v_mov_b32_e32 v135, v130
	v_mov_b32_e32 v129, v131
	v_pk_add_f32 v[132:133], v[194:195], v[132:133]
	v_pk_add_f32 v[128:129], v[134:135], v[128:129]
	v_mov_b32_e32 v131, v132
	v_mov_b32_e32 v130, v128
	v_mov_b32_e32 v132, v129
	v_pk_add_f32 v[128:129], v[130:131], v[132:133]
	ds_bpermute_b32 v163, v219, v161
	ds_bpermute_b32 v162, v219, v160
	ds_bpermute_b32 v131, v219, v129
	ds_bpermute_b32 v130, v219, v128
	ds_bpermute_b32 v171, v218, v169
	ds_bpermute_b32 v170, v218, v168
	s_waitcnt lgkmcnt(4)
	v_pk_add_f32 v[160:161], v[160:161], v[162:163]
	ds_bpermute_b32 v163, v218, v161
	s_waitcnt lgkmcnt(3)
	v_pk_add_f32 v[132:133], v[128:129], v[130:131]
	ds_bpermute_b32 v162, v218, v160
	ds_bpermute_b32 v135, v218, v133
	ds_bpermute_b32 v134, v218, v132
	v_lshlrev_b32_e32 v128, 3, v188
	v_add_u32_e32 v130, s7, v128
	v_lshlrev_b64 v[188:189], 11, v[148:149]
	v_ashrrev_i32_e32 v131, 31, v130
	s_cbranch_scc1 .LBB0_137
	v_mul_f32_e32 v196, v120, v174
	v_mul_f32_e32 v197, v121, v174
	v_mul_f32_e32 v198, v122, v174
	v_mul_f32_e32 v199, v123, v174
	v_mul_f32_e32 v129, v124, v174
	v_mul_f32_e32 v149, v125, v174
	v_mul_f32_e32 v173, v126, v174
	v_mul_f32_e32 v193, v127, v174
	v_cvt_pk_bf16_f32 v194, v129, v149
	v_cvt_pk_bf16_f32 v195, v173, v193
	v_cvt_pk_bf16_f32 v196, v196, v197
	v_cvt_pk_bf16_f32 v197, v198, v199
	v_lshl_add_u64 v[198:199], s[12:13], 0, v[188:189]
	v_lshl_add_u64 v[198:199], v[130:131], 1, v[198:199]
	global_store_dwordx4 v[198:199], v[194:197], off
	s_mov_b64 s[68:69], 0
	v_mul_f32_e32 v129, v116, v174
	v_mul_f32_e32 v196, v112, v174
	v_mul_f32_e32 v197, v113, v174
	v_mul_f32_e32 v149, v117, v174
	v_mul_f32_e32 v173, v118, v174
	v_mul_f32_e32 v193, v119, v174
	v_mul_f32_e32 v200, v114, v174
	v_mul_f32_e32 v201, v115, v174
	v_cvt_pk_bf16_f32 v194, v129, v149
	v_cvt_pk_bf16_f32 v195, v173, v193
	v_cvt_pk_bf16_f32 v196, v196, v197
	v_cvt_pk_bf16_f32 v197, v200, v201
	global_store_dwordx4 v[198:199], v[194:197], off offset:256

.LBB0_413:
	s_add_i32 vcc_lo, s62, 2
	s_add_u32 s4, s18, 0x100
	s_addc_u32 s5, s19, 0
	s_add_i32 s28, 0, 0x10000
	v_add_u32_e32 v140, s28, v164
	ds_read_b128 v[128:131], v140
	ds_read_b128 v[132:135], v140 offset:1024
	ds_read_b128 v[136:139], v140 offset:2048
	ds_read_b128 v[140:143], v140 offset:3072
	s_cmp_eq_u32 s13, s62
	s_cselect_b32 s62, s6, s85
	s_cselect_b32 s65, s17, s5
	s_cselect_b32 s64, s16, s4
	s_cselect_b32 s63, s7, s91
	v_lshl_add_u64 v[174:175], s[18:19], 0, v[150:151]
	s_add_i32 m0, s69, 0xc000
	ds_read_b128 v[154:157], v165
	ds_read_b128 v[166:169], v165 offset:2048
	ds_read_b128 v[188:191], v165 offset:4096
	ds_read_b128 v[196:199], v165 offset:6144
	ds_read_b128 v[158:161], v165 offset:1024
	ds_read_b128 v[170:173], v165 offset:3072
	ds_read_b128 v[192:195], v165 offset:5120
	ds_read_b128 v[200:203], v165 offset:7168
	global_load_lds_dwordx4 v[174:175], off
	v_lshl_add_u64 v[174:175], s[18:19], 0, v[152:153]
	s_add_i32 m0, s69, 0xe000
	s_nop 0
	global_load_lds_dwordx4 v[174:175], off
	s_waitcnt lgkmcnt(8)
	s_barrier
	s_waitcnt lgkmcnt(6)
	v_mfma_f32_16x16x32_bf16 v[124:127], v[128:131], v[154:157], v[124:127]
	v_mfma_f32_16x16x32_bf16 v[120:123], v[136:139], v[154:157], v[120:123]
	v_mfma_f32_16x16x32_bf16 v[108:111], v[128:131], v[166:169], v[108:111]
	v_mfma_f32_16x16x32_bf16 v[104:107], v[136:139], v[166:169], v[104:107]
	s_waitcnt lgkmcnt(4)
	v_mfma_f32_16x16x32_bf16 v[92:95], v[128:131], v[188:191], v[92:95]
	v_mfma_f32_16x16x32_bf16 v[88:91], v[136:139], v[188:191], v[88:91]
	v_mfma_f32_16x16x32_bf16 v[76:79], v[128:131], v[196:199], v[76:79]
	v_mfma_f32_16x16x32_bf16 v[72:75], v[136:139], v[196:199], v[72:75]
	s_waitcnt lgkmcnt(2)
	v_mfma_f32_16x16x32_bf16 v[124:127], v[132:135], v[158:161], v[124:127]
	v_mfma_f32_16x16x32_bf16 v[120:123], v[140:143], v[158:161], v[120:123]
	v_mfma_f32_16x16x32_bf16 v[108:111], v[132:135], v[170:173], v[108:111]
	v_mfma_f32_16x16x32_bf16 v[104:107], v[140:143], v[170:173], v[104:107]
	s_waitcnt lgkmcnt(0)
	v_mfma_f32_16x16x32_bf16 v[92:95], v[132:135], v[192:195], v[92:95]
	v_mfma_f32_16x16x32_bf16 v[88:91], v[140:143], v[192:195], v[88:91]
	v_mfma_f32_16x16x32_bf16 v[76:79], v[132:135], v[200:203], v[76:79]
	v_mfma_f32_16x16x32_bf16 v[72:75], v[140:143], v[200:203], v[72:75]
	s_barrier
	s_add_i32 s29, 0, 0x14000
	v_add_u32_e32 v174, s29, v164
	s_add_i32 s18, s28, s68
	ds_read_b128 v[204:207], v174
	ds_read_b128 v[208:211], v174 offset:1024
	ds_read_b128 v[212:215], v174 offset:2048
	ds_read_b128 v[232:235], v174 offset:3072
	v_lshl_add_u64 v[174:175], s[62:63], 0, v[176:177]
	s_mov_b32 m0, s18
	v_lshl_add_u64 v[216:217], s[62:63], 0, v[148:149]
	global_load_lds_dwordx4 v[174:175], off
	s_add_i32 m0, s18, 0x2000
	s_nop 0
	global_load_lds_dwordx4 v[216:217], off
	s_barrier
	s_waitcnt lgkmcnt(1)
	v_mfma_f32_16x16x32_bf16 v[116:119], v[204:207], v[154:157], v[116:119]
	v_mfma_f32_16x16x32_bf16 v[112:115], v[212:215], v[154:157], v[112:115]
	v_mfma_f32_16x16x32_bf16 v[100:103], v[204:207], v[166:169], v[100:103]
	v_mfma_f32_16x16x32_bf16 v[96:99], v[212:215], v[166:169], v[96:99]
	v_mfma_f32_16x16x32_bf16 v[84:87], v[204:207], v[188:191], v[84:87]
	v_mfma_f32_16x16x32_bf16 v[80:83], v[212:215], v[188:191], v[80:83]
	v_mfma_f32_16x16x32_bf16 v[68:71], v[204:207], v[196:199], v[68:71]
	v_mfma_f32_16x16x32_bf16 v[64:67], v[212:215], v[196:199], v[64:67]
	s_waitcnt lgkmcnt(0)
	v_mfma_f32_16x16x32_bf16 v[116:119], v[208:211], v[158:161], v[116:119]
	v_mfma_f32_16x16x32_bf16 v[112:115], v[232:235], v[158:161], v[112:115]
	v_mfma_f32_16x16x32_bf16 v[100:103], v[208:211], v[170:173], v[100:103]
	v_mfma_f32_16x16x32_bf16 v[96:99], v[232:235], v[170:173], v[96:99]
	v_mfma_f32_16x16x32_bf16 v[84:87], v[208:211], v[192:195], v[84:87]
	v_mfma_f32_16x16x32_bf16 v[80:83], v[232:235], v[192:195], v[80:83]
	v_mfma_f32_16x16x32_bf16 v[68:71], v[208:211], v[200:203], v[68:71]
	v_mfma_f32_16x16x32_bf16 v[64:67], v[232:235], v[200:203], v[64:67]
	s_mov_b32 m0, s69
	v_lshl_add_u64 v[236:237], s[64:65], 0, v[144:145]
	s_barrier
	ds_read_b128 v[154:157], v165 offset:16384
	ds_read_b128 v[166:169], v165 offset:18432
	ds_read_b128 v[188:191], v165 offset:20480
	ds_read_b128 v[196:199], v165 offset:22528
	ds_read_b128 v[158:161], v165 offset:17408
	ds_read_b128 v[170:173], v165 offset:19456
	ds_read_b128 v[192:195], v165 offset:21504
	ds_read_b128 v[200:203], v165 offset:23552
	global_load_lds_dwordx4 v[236:237], off
	v_lshl_add_u64 v[238:239], s[64:65], 0, v[146:147]
	s_mov_b32 m0, s70
	s_nop 0
	global_load_lds_dwordx4 v[238:239], off
	s_barrier
	s_waitcnt lgkmcnt(6)
	v_mfma_f32_16x16x32_bf16 v[60:63], v[128:131], v[154:157], v[60:63]
	v_mfma_f32_16x16x32_bf16 v[56:59], v[136:139], v[154:157], v[56:59]
	v_mfma_f32_16x16x32_bf16 v[44:47], v[128:131], v[166:169], v[44:47]
	v_mfma_f32_16x16x32_bf16 v[40:43], v[136:139], v[166:169], v[40:43]
	s_waitcnt lgkmcnt(4)
	v_mfma_f32_16x16x32_bf16 v[28:31], v[128:131], v[188:191], v[28:31]
	v_mfma_f32_16x16x32_bf16 v[24:27], v[136:139], v[188:191], v[24:27]
	v_mfma_f32_16x16x32_bf16 v[12:15], v[128:131], v[196:199], v[12:15]
	v_mfma_f32_16x16x32_bf16 v[8:11], v[136:139], v[196:199], v[8:11]
	s_waitcnt lgkmcnt(2)
	v_mfma_f32_16x16x32_bf16 v[60:63], v[132:135], v[158:161], v[60:63]
	v_mfma_f32_16x16x32_bf16 v[56:59], v[140:143], v[158:161], v[56:59]
	v_mfma_f32_16x16x32_bf16 v[44:47], v[132:135], v[170:173], v[44:47]
	v_mfma_f32_16x16x32_bf16 v[40:43], v[140:143], v[170:173], v[40:43]
	s_waitcnt lgkmcnt(0)
	v_mfma_f32_16x16x32_bf16 v[28:31], v[132:135], v[192:195], v[28:31]
	v_mfma_f32_16x16x32_bf16 v[24:27], v[140:143], v[192:195], v[24:27]
	v_mfma_f32_16x16x32_bf16 v[12:15], v[132:135], v[200:203], v[12:15]
	v_mfma_f32_16x16x32_bf16 v[8:11], v[140:143], v[200:203], v[8:11]
	s_barrier
	s_add_u32 s18, s62, 0x18000
	s_addc_u32 s19, s63, 0
	s_add_i32 s28, s29, s68
	v_lshl_add_u64 v[128:129], s[18:19], 0, v[176:177]
	s_mov_b32 m0, s28
	s_nop 0
	global_load_lds_dwordx4 v[128:129], off
	v_lshl_add_u64 v[128:129], s[18:19], 0, v[148:149]
	s_add_i32 m0, s28, 0x2000
	s_nop 0
	global_load_lds_dwordx4 v[128:129], off
	s_waitcnt vmcnt(6)
	s_barrier
	v_mfma_f32_16x16x32_bf16 v[52:55], v[204:207], v[154:157], v[52:55]
	v_mfma_f32_16x16x32_bf16 v[48:51], v[212:215], v[154:157], v[48:51]
	v_mfma_f32_16x16x32_bf16 v[36:39], v[204:207], v[166:169], v[36:39]
	v_mfma_f32_16x16x32_bf16 v[32:35], v[212:215], v[166:169], v[32:35]
	v_mfma_f32_16x16x32_bf16 v[20:23], v[204:207], v[188:191], v[20:23]
	v_mfma_f32_16x16x32_bf16 v[16:19], v[212:215], v[188:191], v[16:19]
	v_mfma_f32_16x16x32_bf16 v[4:7], v[204:207], v[196:199], v[4:7]
	v_mfma_f32_16x16x32_bf16 v[0:3], v[212:215], v[196:199], v[0:3]
	v_mfma_f32_16x16x32_bf16 v[52:55], v[208:211], v[158:161], v[52:55]
	v_mfma_f32_16x16x32_bf16 v[48:51], v[232:235], v[158:161], v[48:51]
	v_mfma_f32_16x16x32_bf16 v[36:39], v[208:211], v[170:173], v[36:39]
	v_mfma_f32_16x16x32_bf16 v[32:35], v[232:235], v[170:173], v[32:35]
	v_mfma_f32_16x16x32_bf16 v[20:23], v[208:211], v[192:195], v[20:23]
	v_mfma_f32_16x16x32_bf16 v[16:19], v[232:235], v[192:195], v[16:19]
	v_mfma_f32_16x16x32_bf16 v[4:7], v[208:211], v[200:203], v[4:7]
	v_mfma_f32_16x16x32_bf16 v[0:3], v[232:235], v[200:203], v[0:3]
	s_add_i32 s28, 0, 0x18000
	v_add_u32_e32 v140, s28, v164
	s_barrier
	ds_read_b128 v[128:131], v140
	ds_read_b128 v[132:135], v140 offset:1024
	ds_read_b128 v[136:139], v140 offset:2048
	ds_read_b128 v[140:143], v140 offset:3072
	s_add_u32 s18, s64, 0x18000
	s_addc_u32 s19, s65, 0
	s_mov_b32 m0, s71
	v_lshl_add_u64 v[204:205], s[18:19], 0, v[144:145]
	ds_read_b128 v[154:157], v165 offset:32768
	ds_read_b128 v[166:169], v165 offset:34816
	ds_read_b128 v[188:191], v165 offset:36864
	ds_read_b128 v[196:199], v165 offset:38912
	ds_read_b128 v[158:161], v165 offset:33792
	ds_read_b128 v[170:173], v165 offset:35840
	ds_read_b128 v[192:195], v165 offset:37888
	ds_read_b128 v[200:203], v165 offset:39936
	global_load_lds_dwordx4 v[204:205], off
	v_lshl_add_u64 v[204:205], s[18:19], 0, v[146:147]
	s_mov_b32 m0, s72
	s_nop 0
	global_load_lds_dwordx4 v[204:205], off
	s_waitcnt lgkmcnt(8)
	s_barrier
	s_waitcnt lgkmcnt(6)
	v_mfma_f32_16x16x32_bf16 v[124:127], v[128:131], v[154:157], v[124:127]
	v_mfma_f32_16x16x32_bf16 v[120:123], v[136:139], v[154:157], v[120:123]
	v_mfma_f32_16x16x32_bf16 v[108:111], v[128:131], v[166:169], v[108:111]
	v_mfma_f32_16x16x32_bf16 v[104:107], v[136:139], v[166:169], v[104:107]
	s_waitcnt lgkmcnt(4)
	v_mfma_f32_16x16x32_bf16 v[92:95], v[128:131], v[188:191], v[92:95]
	v_mfma_f32_16x16x32_bf16 v[88:91], v[136:139], v[188:191], v[88:91]
	v_mfma_f32_16x16x32_bf16 v[76:79], v[128:131], v[196:199], v[76:79]
	v_mfma_f32_16x16x32_bf16 v[72:75], v[136:139], v[196:199], v[72:75]
	s_waitcnt lgkmcnt(2)
	v_mfma_f32_16x16x32_bf16 v[124:127], v[132:135], v[158:161], v[124:127]
	v_mfma_f32_16x16x32_bf16 v[120:123], v[140:143], v[158:161], v[120:123]
	v_mfma_f32_16x16x32_bf16 v[108:111], v[132:135], v[170:173], v[108:111]
	v_mfma_f32_16x16x32_bf16 v[104:107], v[140:143], v[170:173], v[104:107]
	s_waitcnt lgkmcnt(0)
	v_mfma_f32_16x16x32_bf16 v[92:95], v[132:135], v[192:195], v[92:95]
	v_mfma_f32_16x16x32_bf16 v[88:91], v[140:143], v[192:195], v[88:91]
	v_mfma_f32_16x16x32_bf16 v[76:79], v[132:135], v[200:203], v[76:79]
	v_mfma_f32_16x16x32_bf16 v[72:75], v[140:143], v[200:203], v[72:75]
	s_barrier
	s_add_i32 s29, 0, 0x1c000
	s_add_i32 s18, s28, s68
	v_add_u32_e32 v232, s29, v164
	v_lshl_add_u64 v[174:175], v[174:175], 0, s[40:41]
	s_mov_b32 m0, s18
	ds_read_b128 v[204:207], v232
	ds_read_b128 v[208:211], v232 offset:1024
	ds_read_b128 v[212:215], v232 offset:2048
	ds_read_b128 v[232:235], v232 offset:3072
	global_load_lds_dwordx4 v[174:175], off
	v_lshl_add_u64 v[174:175], v[216:217], 0, s[40:41]
	s_add_i32 m0, s18, 0x2000
	s_nop 0
	global_load_lds_dwordx4 v[174:175], off
	s_barrier
	s_waitcnt lgkmcnt(1)
	v_mfma_f32_16x16x32_bf16 v[116:119], v[204:207], v[154:157], v[116:119]
	v_mfma_f32_16x16x32_bf16 v[112:115], v[212:215], v[154:157], v[112:115]
	v_mfma_f32_16x16x32_bf16 v[100:103], v[204:207], v[166:169], v[100:103]
	v_mfma_f32_16x16x32_bf16 v[96:99], v[212:215], v[166:169], v[96:99]
	v_mfma_f32_16x16x32_bf16 v[84:87], v[204:207], v[188:191], v[84:87]
	v_mfma_f32_16x16x32_bf16 v[80:83], v[212:215], v[188:191], v[80:83]
	v_mfma_f32_16x16x32_bf16 v[68:71], v[204:207], v[196:199], v[68:71]
	v_mfma_f32_16x16x32_bf16 v[64:67], v[212:215], v[196:199], v[64:67]
	s_waitcnt lgkmcnt(0)
	v_mfma_f32_16x16x32_bf16 v[116:119], v[208:211], v[158:161], v[116:119]
	v_mfma_f32_16x16x32_bf16 v[112:115], v[232:235], v[158:161], v[112:115]
	v_mfma_f32_16x16x32_bf16 v[100:103], v[208:211], v[170:173], v[100:103]
	v_mfma_f32_16x16x32_bf16 v[96:99], v[232:235], v[170:173], v[96:99]
	v_mfma_f32_16x16x32_bf16 v[84:87], v[208:211], v[192:195], v[84:87]
	v_mfma_f32_16x16x32_bf16 v[80:83], v[232:235], v[192:195], v[80:83]
	v_mfma_f32_16x16x32_bf16 v[68:71], v[208:211], v[200:203], v[68:71]
	v_mfma_f32_16x16x32_bf16 v[64:67], v[232:235], v[200:203], v[64:67]
	s_mov_b32 m0, s75
	v_lshl_add_u64 v[174:175], v[236:237], 0, s[40:41]
	s_barrier
	ds_read_b128 v[154:157], v165 offset:49152
	ds_read_b128 v[166:169], v165 offset:51200
	ds_read_b128 v[188:191], v165 offset:53248
	ds_read_b128 v[196:199], v165 offset:55296
	ds_read_b128 v[158:161], v165 offset:50176
	ds_read_b128 v[170:173], v165 offset:52224
	ds_read_b128 v[192:195], v165 offset:54272
	ds_read_b128 v[200:203], v165 offset:56320
	global_load_lds_dwordx4 v[174:175], off
	v_lshl_add_u64 v[174:175], v[238:239], 0, s[40:41]
	s_mov_b32 m0, s76
	s_nop 0
	global_load_lds_dwordx4 v[174:175], off
	s_barrier
	s_waitcnt lgkmcnt(6)
	v_mfma_f32_16x16x32_bf16 v[60:63], v[128:131], v[154:157], v[60:63]
	v_mfma_f32_16x16x32_bf16 v[56:59], v[136:139], v[154:157], v[56:59]
	v_mfma_f32_16x16x32_bf16 v[44:47], v[128:131], v[166:169], v[44:47]
	v_mfma_f32_16x16x32_bf16 v[40:43], v[136:139], v[166:169], v[40:43]
	s_waitcnt lgkmcnt(4)
	v_mfma_f32_16x16x32_bf16 v[28:31], v[128:131], v[188:191], v[28:31]
	v_mfma_f32_16x16x32_bf16 v[24:27], v[136:139], v[188:191], v[24:27]
	v_mfma_f32_16x16x32_bf16 v[12:15], v[128:131], v[196:199], v[12:15]
	v_mfma_f32_16x16x32_bf16 v[8:11], v[136:139], v[196:199], v[8:11]
	s_waitcnt lgkmcnt(2)
	v_mfma_f32_16x16x32_bf16 v[60:63], v[132:135], v[158:161], v[60:63]
	v_mfma_f32_16x16x32_bf16 v[56:59], v[140:143], v[158:161], v[56:59]
	v_mfma_f32_16x16x32_bf16 v[44:47], v[132:135], v[170:173], v[44:47]
	v_mfma_f32_16x16x32_bf16 v[40:43], v[140:143], v[170:173], v[40:43]
	s_waitcnt lgkmcnt(0)
	v_mfma_f32_16x16x32_bf16 v[28:31], v[132:135], v[192:195], v[28:31]
	v_mfma_f32_16x16x32_bf16 v[24:27], v[140:143], v[192:195], v[24:27]
	v_mfma_f32_16x16x32_bf16 v[12:15], v[132:135], v[200:203], v[12:15]
	v_mfma_f32_16x16x32_bf16 v[8:11], v[140:143], v[200:203], v[8:11]
	s_barrier
	s_add_u32 s18, s62, 0x18080
	s_addc_u32 s19, s63, 0
	s_add_i32 s28, s29, s68
	v_lshl_add_u64 v[128:129], s[18:19], 0, v[176:177]
	s_mov_b32 m0, s28
	s_nop 0
	global_load_lds_dwordx4 v[128:129], off
	v_lshl_add_u64 v[128:129], s[18:19], 0, v[148:149]
	s_add_i32 m0, s28, 0x2000
	s_nop 0
	global_load_lds_dwordx4 v[128:129], off
	s_waitcnt vmcnt(6)
	s_barrier
	v_mfma_f32_16x16x32_bf16 v[52:55], v[204:207], v[154:157], v[52:55]
	v_mfma_f32_16x16x32_bf16 v[48:51], v[212:215], v[154:157], v[48:51]
	v_mfma_f32_16x16x32_bf16 v[36:39], v[204:207], v[166:169], v[36:39]
	v_mfma_f32_16x16x32_bf16 v[32:35], v[212:215], v[166:169], v[32:35]
	v_mfma_f32_16x16x32_bf16 v[20:23], v[204:207], v[188:191], v[20:23]
	v_mfma_f32_16x16x32_bf16 v[16:19], v[212:215], v[188:191], v[16:19]
	v_mfma_f32_16x16x32_bf16 v[4:7], v[204:207], v[196:199], v[4:7]
	v_mfma_f32_16x16x32_bf16 v[0:3], v[212:215], v[196:199], v[0:3]
	v_mfma_f32_16x16x32_bf16 v[52:55], v[208:211], v[158:161], v[52:55]
	v_mfma_f32_16x16x32_bf16 v[48:51], v[232:235], v[158:161], v[48:51]
	v_mfma_f32_16x16x32_bf16 v[36:39], v[208:211], v[170:173], v[36:39]
	v_mfma_f32_16x16x32_bf16 v[32:35], v[232:235], v[170:173], v[32:35]
	v_mfma_f32_16x16x32_bf16 v[20:23], v[208:211], v[192:195], v[20:23]
	v_mfma_f32_16x16x32_bf16 v[16:19], v[232:235], v[192:195], v[16:19]
	v_mfma_f32_16x16x32_bf16 v[4:7], v[208:211], v[200:203], v[4:7]
	v_mfma_f32_16x16x32_bf16 v[0:3], v[232:235], v[200:203], v[0:3]
	s_add_u32 s85, s85, 0x100
	s_addc_u32 s91, s91, 0
	s_cmp_lt_i32 vcc_lo, s67
	s_mov_b64 s[18:19], s[4:5]
	s_mov_b32 s62, vcc_lo
	s_barrier
	s_cbranch_scc1 .LBB0_413
	s_ashr_i32 s4, s66, 2
	v_mov_b32_e32 v128, v163
	v_mov_b32_e32 v166, v162
	s_cmp_eq_u32 s4, 2
	s_cbranch_scc1 .LBB0_416
	s_mul_i32 s13, s4, 0x2280000
	s_mul_hi_i32 s5, s4, 0x2280000
	s_add_u32 s18, s13, 0x5858000
	s_addc_u32 s19, s5, 0
	s_mov_b32 s62, 1.0
	s_branch .LBB0_417

.LBB0_505:
	s_add_u32 s6, s4, 0xfff80080
	s_addc_u32 s7, s5, -1
	s_add_i32 s28, 0, 0x10000
	v_add_u32_e32 v154, s28, v144
	ds_read_b128 v[138:141], v154
	ds_read_b128 v[146:149], v154 offset:1024
	ds_read_b128 v[150:153], v154 offset:2048
	ds_read_b128 v[154:157], v154 offset:3072
	s_cmp_eq_u32 s72, 28
	s_cselect_b32 s9, s10, s7
	s_cselect_b32 s8, s11, s6
	s_cselect_b32 s7, s63, s71
	s_cselect_b32 s6, s65, s70
	v_lshl_add_u64 v[174:175], s[4:5], 0, v[134:135]
	s_add_i32 m0, s17, 0xc000
	ds_read_b128 v[158:161], v145
	ds_read_b128 v[166:169], v145 offset:2048
	ds_read_b128 v[188:191], v145 offset:4096
	ds_read_b128 v[196:199], v145 offset:6144
	ds_read_b128 v[162:165], v145 offset:1024
	ds_read_b128 v[170:173], v145 offset:3072
	ds_read_b128 v[192:195], v145 offset:5120
	ds_read_b128 v[200:203], v145 offset:7168
	global_load_lds_dwordx4 v[174:175], off
	v_lshl_add_u64 v[174:175], s[4:5], 0, v[136:137]
	s_add_i32 m0, s17, 0xe000
	s_nop 0
	global_load_lds_dwordx4 v[174:175], off
	s_waitcnt lgkmcnt(8)
	s_barrier
	s_waitcnt lgkmcnt(6)
	v_mfma_f32_16x16x32_bf16 v[124:127], v[138:141], v[158:161], v[124:127]
	v_mfma_f32_16x16x32_bf16 v[120:123], v[150:153], v[158:161], v[120:123]
	v_mfma_f32_16x16x32_bf16 v[116:119], v[138:141], v[166:169], v[116:119]
	v_mfma_f32_16x16x32_bf16 v[108:111], v[150:153], v[166:169], v[108:111]
	s_waitcnt lgkmcnt(4)
	v_mfma_f32_16x16x32_bf16 v[100:103], v[138:141], v[188:191], v[100:103]
	v_mfma_f32_16x16x32_bf16 v[92:95], v[150:153], v[188:191], v[92:95]
	v_mfma_f32_16x16x32_bf16 v[84:87], v[138:141], v[196:199], v[84:87]
	v_mfma_f32_16x16x32_bf16 v[76:79], v[150:153], v[196:199], v[76:79]
	s_waitcnt lgkmcnt(2)
	v_mfma_f32_16x16x32_bf16 v[124:127], v[146:149], v[162:165], v[124:127]
	v_mfma_f32_16x16x32_bf16 v[120:123], v[154:157], v[162:165], v[120:123]
	v_mfma_f32_16x16x32_bf16 v[116:119], v[146:149], v[170:173], v[116:119]
	v_mfma_f32_16x16x32_bf16 v[108:111], v[154:157], v[170:173], v[108:111]
	s_waitcnt lgkmcnt(0)
	v_mfma_f32_16x16x32_bf16 v[100:103], v[146:149], v[192:195], v[100:103]
	v_mfma_f32_16x16x32_bf16 v[92:95], v[154:157], v[192:195], v[92:95]
	v_mfma_f32_16x16x32_bf16 v[84:87], v[146:149], v[200:203], v[84:87]
	v_mfma_f32_16x16x32_bf16 v[76:79], v[154:157], v[200:203], v[76:79]
	s_barrier
	s_add_i32 s29, 0, 0x14000
	v_add_u32_e32 v174, s29, v144
	s_add_i32 s28, s28, s77
	ds_read_b128 v[204:207], v174
	ds_read_b128 v[208:211], v174 offset:1024
	ds_read_b128 v[212:215], v174 offset:2048
	ds_read_b128 v[232:235], v174 offset:3072
	v_lshl_add_u64 v[174:175], s[6:7], 0, v[176:177]
	s_mov_b32 m0, s28
	v_lshl_add_u64 v[216:217], s[6:7], 0, v[132:133]
	global_load_lds_dwordx4 v[174:175], off
	s_add_i32 m0, s28, 0x2000
	s_nop 0
	global_load_lds_dwordx4 v[216:217], off
	s_barrier
	s_waitcnt lgkmcnt(1)
	v_mfma_f32_16x16x32_bf16 v[112:115], v[204:207], v[158:161], v[112:115]
	v_mfma_f32_16x16x32_bf16 v[104:107], v[212:215], v[158:161], v[104:107]
	v_mfma_f32_16x16x32_bf16 v[96:99], v[204:207], v[166:169], v[96:99]
	v_mfma_f32_16x16x32_bf16 v[88:91], v[212:215], v[166:169], v[88:91]
	v_mfma_f32_16x16x32_bf16 v[80:83], v[204:207], v[188:191], v[80:83]
	v_mfma_f32_16x16x32_bf16 v[72:75], v[212:215], v[188:191], v[72:75]
	v_mfma_f32_16x16x32_bf16 v[68:71], v[204:207], v[196:199], v[68:71]
	v_mfma_f32_16x16x32_bf16 v[64:67], v[212:215], v[196:199], v[64:67]
	s_waitcnt lgkmcnt(0)
	v_mfma_f32_16x16x32_bf16 v[112:115], v[208:211], v[162:165], v[112:115]
	v_mfma_f32_16x16x32_bf16 v[104:107], v[232:235], v[162:165], v[104:107]
	v_mfma_f32_16x16x32_bf16 v[96:99], v[208:211], v[170:173], v[96:99]
	v_mfma_f32_16x16x32_bf16 v[88:91], v[232:235], v[170:173], v[88:91]
	v_mfma_f32_16x16x32_bf16 v[80:83], v[208:211], v[192:195], v[80:83]
	v_mfma_f32_16x16x32_bf16 v[72:75], v[232:235], v[192:195], v[72:75]
	v_mfma_f32_16x16x32_bf16 v[68:71], v[208:211], v[200:203], v[68:71]
	v_mfma_f32_16x16x32_bf16 v[64:67], v[232:235], v[200:203], v[64:67]
	s_mov_b32 m0, s17
	v_lshl_add_u64 v[236:237], s[8:9], 0, v[128:129]
	s_barrier
	ds_read_b128 v[158:161], v145 offset:16384
	ds_read_b128 v[166:169], v145 offset:18432
	ds_read_b128 v[188:191], v145 offset:20480
	ds_read_b128 v[196:199], v145 offset:22528
	ds_read_b128 v[162:165], v145 offset:17408
	ds_read_b128 v[170:173], v145 offset:19456
	ds_read_b128 v[192:195], v145 offset:21504
	ds_read_b128 v[200:203], v145 offset:23552
	global_load_lds_dwordx4 v[236:237], off
	v_lshl_add_u64 v[238:239], s[8:9], 0, v[130:131]
	s_mov_b32 m0, s19
	s_nop 0
	global_load_lds_dwordx4 v[238:239], off
	s_barrier
	s_waitcnt lgkmcnt(6)
	v_mfma_f32_16x16x32_bf16 v[60:63], v[138:141], v[158:161], v[60:63]
	v_mfma_f32_16x16x32_bf16 v[56:59], v[150:153], v[158:161], v[56:59]
	v_mfma_f32_16x16x32_bf16 v[52:55], v[138:141], v[166:169], v[52:55]
	v_mfma_f32_16x16x32_bf16 v[44:47], v[150:153], v[166:169], v[44:47]
	s_waitcnt lgkmcnt(4)
	v_mfma_f32_16x16x32_bf16 v[36:39], v[138:141], v[188:191], v[36:39]
	v_mfma_f32_16x16x32_bf16 v[28:31], v[150:153], v[188:191], v[28:31]
	v_mfma_f32_16x16x32_bf16 v[20:23], v[138:141], v[196:199], v[20:23]
	v_mfma_f32_16x16x32_bf16 v[12:15], v[150:153], v[196:199], v[12:15]
	s_waitcnt lgkmcnt(2)
	v_mfma_f32_16x16x32_bf16 v[60:63], v[146:149], v[162:165], v[60:63]
	v_mfma_f32_16x16x32_bf16 v[56:59], v[154:157], v[162:165], v[56:59]
	v_mfma_f32_16x16x32_bf16 v[52:55], v[146:149], v[170:173], v[52:55]
	v_mfma_f32_16x16x32_bf16 v[44:47], v[154:157], v[170:173], v[44:47]
	s_waitcnt lgkmcnt(0)
	v_mfma_f32_16x16x32_bf16 v[36:39], v[146:149], v[192:195], v[36:39]
	v_mfma_f32_16x16x32_bf16 v[28:31], v[154:157], v[192:195], v[28:31]
	v_mfma_f32_16x16x32_bf16 v[20:23], v[146:149], v[200:203], v[20:23]
	v_mfma_f32_16x16x32_bf16 v[12:15], v[154:157], v[200:203], v[12:15]
	s_barrier
	s_add_u32 vcc_lo, s6, 0x80000
	s_addc_u32 vcc_hi, s7, 0
	s_add_i32 s28, s29, s77
	v_lshl_add_u64 v[138:139], vcc, 0, v[176:177]
	s_mov_b32 m0, s28
	s_nop 0
	global_load_lds_dwordx4 v[138:139], off
	v_lshl_add_u64 v[138:139], vcc, 0, v[132:133]
	s_add_i32 m0, s28, 0x2000
	s_nop 0
	global_load_lds_dwordx4 v[138:139], off
	s_waitcnt vmcnt(6)
	s_barrier
	v_mfma_f32_16x16x32_bf16 v[48:51], v[204:207], v[158:161], v[48:51]
	v_mfma_f32_16x16x32_bf16 v[40:43], v[212:215], v[158:161], v[40:43]
	v_mfma_f32_16x16x32_bf16 v[32:35], v[204:207], v[166:169], v[32:35]
	v_mfma_f32_16x16x32_bf16 v[24:27], v[212:215], v[166:169], v[24:27]
	v_mfma_f32_16x16x32_bf16 v[16:19], v[204:207], v[188:191], v[16:19]
	v_mfma_f32_16x16x32_bf16 v[8:11], v[212:215], v[188:191], v[8:11]
	v_mfma_f32_16x16x32_bf16 v[4:7], v[204:207], v[196:199], v[4:7]
	v_mfma_f32_16x16x32_bf16 v[0:3], v[212:215], v[196:199], v[0:3]
	v_mfma_f32_16x16x32_bf16 v[48:51], v[208:211], v[162:165], v[48:51]
	v_mfma_f32_16x16x32_bf16 v[40:43], v[232:235], v[162:165], v[40:43]
	v_mfma_f32_16x16x32_bf16 v[32:35], v[208:211], v[170:173], v[32:35]
	v_mfma_f32_16x16x32_bf16 v[24:27], v[232:235], v[170:173], v[24:27]
	v_mfma_f32_16x16x32_bf16 v[16:19], v[208:211], v[192:195], v[16:19]
	v_mfma_f32_16x16x32_bf16 v[8:11], v[232:235], v[192:195], v[8:11]
	v_mfma_f32_16x16x32_bf16 v[4:7], v[208:211], v[200:203], v[4:7]
	v_mfma_f32_16x16x32_bf16 v[0:3], v[232:235], v[200:203], v[0:3]
	s_add_i32 s28, 0, 0x18000
	v_add_u32_e32 v154, s28, v144
	s_barrier
	ds_read_b128 v[138:141], v154
	ds_read_b128 v[146:149], v154 offset:1024
	ds_read_b128 v[150:153], v154 offset:2048
	ds_read_b128 v[154:157], v154 offset:3072
	s_add_u32 s8, s8, 0x80000
	s_addc_u32 s9, s9, 0
	s_mov_b32 m0, s78
	v_lshl_add_u64 v[204:205], s[8:9], 0, v[128:129]
	ds_read_b128 v[158:161], v145 offset:32768
	ds_read_b128 v[166:169], v145 offset:34816
	ds_read_b128 v[188:191], v145 offset:36864
	ds_read_b128 v[196:199], v145 offset:38912
	ds_read_b128 v[162:165], v145 offset:33792
	ds_read_b128 v[170:173], v145 offset:35840
	ds_read_b128 v[192:195], v145 offset:37888
	ds_read_b128 v[200:203], v145 offset:39936
	global_load_lds_dwordx4 v[204:205], off
	v_lshl_add_u64 v[204:205], s[8:9], 0, v[130:131]
	s_mov_b32 m0, s79
	s_nop 0
	global_load_lds_dwordx4 v[204:205], off
	s_waitcnt lgkmcnt(8)
	s_barrier
	s_waitcnt lgkmcnt(6)
	v_mfma_f32_16x16x32_bf16 v[124:127], v[138:141], v[158:161], v[124:127]
	v_mfma_f32_16x16x32_bf16 v[120:123], v[150:153], v[158:161], v[120:123]
	v_mfma_f32_16x16x32_bf16 v[116:119], v[138:141], v[166:169], v[116:119]
	v_mfma_f32_16x16x32_bf16 v[108:111], v[150:153], v[166:169], v[108:111]
	s_waitcnt lgkmcnt(4)
	v_mfma_f32_16x16x32_bf16 v[100:103], v[138:141], v[188:191], v[100:103]
	v_mfma_f32_16x16x32_bf16 v[92:95], v[150:153], v[188:191], v[92:95]
	v_mfma_f32_16x16x32_bf16 v[84:87], v[138:141], v[196:199], v[84:87]
	v_mfma_f32_16x16x32_bf16 v[76:79], v[150:153], v[196:199], v[76:79]
	s_waitcnt lgkmcnt(2)
	v_mfma_f32_16x16x32_bf16 v[124:127], v[146:149], v[162:165], v[124:127]
	v_mfma_f32_16x16x32_bf16 v[120:123], v[154:157], v[162:165], v[120:123]
	v_mfma_f32_16x16x32_bf16 v[116:119], v[146:149], v[170:173], v[116:119]
	v_mfma_f32_16x16x32_bf16 v[108:111], v[154:157], v[170:173], v[108:111]
	s_waitcnt lgkmcnt(0)
	v_mfma_f32_16x16x32_bf16 v[100:103], v[146:149], v[192:195], v[100:103]
	v_mfma_f32_16x16x32_bf16 v[92:95], v[154:157], v[192:195], v[92:95]
	v_mfma_f32_16x16x32_bf16 v[84:87], v[146:149], v[200:203], v[84:87]
	v_mfma_f32_16x16x32_bf16 v[76:79], v[154:157], v[200:203], v[76:79]
	s_barrier
	s_add_i32 s8, 0, 0x1c000
	s_add_i32 s9, s28, s77
	v_add_u32_e32 v232, s8, v144
	v_lshl_add_u64 v[174:175], v[174:175], 0, s[40:41]
	s_mov_b32 m0, s9
	ds_read_b128 v[204:207], v232
	ds_read_b128 v[208:211], v232 offset:1024
	ds_read_b128 v[212:215], v232 offset:2048
	ds_read_b128 v[232:235], v232 offset:3072
	global_load_lds_dwordx4 v[174:175], off
	v_lshl_add_u64 v[174:175], v[216:217], 0, s[40:41]
	s_add_i32 m0, s9, 0x2000
	s_nop 0
	global_load_lds_dwordx4 v[174:175], off
	s_barrier
	s_waitcnt lgkmcnt(1)
	v_mfma_f32_16x16x32_bf16 v[112:115], v[204:207], v[158:161], v[112:115]
	v_mfma_f32_16x16x32_bf16 v[104:107], v[212:215], v[158:161], v[104:107]
	v_mfma_f32_16x16x32_bf16 v[96:99], v[204:207], v[166:169], v[96:99]
	v_mfma_f32_16x16x32_bf16 v[88:91], v[212:215], v[166:169], v[88:91]
	v_mfma_f32_16x16x32_bf16 v[80:83], v[204:207], v[188:191], v[80:83]
	v_mfma_f32_16x16x32_bf16 v[72:75], v[212:215], v[188:191], v[72:75]
	v_mfma_f32_16x16x32_bf16 v[68:71], v[204:207], v[196:199], v[68:71]
	v_mfma_f32_16x16x32_bf16 v[64:67], v[212:215], v[196:199], v[64:67]
	s_waitcnt lgkmcnt(0)
	v_mfma_f32_16x16x32_bf16 v[112:115], v[208:211], v[162:165], v[112:115]
	v_mfma_f32_16x16x32_bf16 v[104:107], v[232:235], v[162:165], v[104:107]
	v_mfma_f32_16x16x32_bf16 v[96:99], v[208:211], v[170:173], v[96:99]
	v_mfma_f32_16x16x32_bf16 v[88:91], v[232:235], v[170:173], v[88:91]
	v_mfma_f32_16x16x32_bf16 v[80:83], v[208:211], v[192:195], v[80:83]
	v_mfma_f32_16x16x32_bf16 v[72:75], v[232:235], v[192:195], v[72:75]
	v_mfma_f32_16x16x32_bf16 v[68:71], v[208:211], v[200:203], v[68:71]
	v_mfma_f32_16x16x32_bf16 v[64:67], v[232:235], v[200:203], v[64:67]
	s_mov_b32 m0, s82
	v_lshl_add_u64 v[174:175], v[236:237], 0, s[40:41]
	s_barrier
	ds_read_b128 v[158:161], v145 offset:49152
	ds_read_b128 v[166:169], v145 offset:51200
	ds_read_b128 v[188:191], v145 offset:53248
	ds_read_b128 v[196:199], v145 offset:55296
	ds_read_b128 v[162:165], v145 offset:50176
	ds_read_b128 v[170:173], v145 offset:52224
	ds_read_b128 v[192:195], v145 offset:54272
	ds_read_b128 v[200:203], v145 offset:56320
	global_load_lds_dwordx4 v[174:175], off
	v_lshl_add_u64 v[174:175], v[238:239], 0, s[40:41]
	s_mov_b32 m0, s83
	s_nop 0
	global_load_lds_dwordx4 v[174:175], off
	s_barrier
	s_waitcnt lgkmcnt(6)
	v_mfma_f32_16x16x32_bf16 v[60:63], v[138:141], v[158:161], v[60:63]
	v_mfma_f32_16x16x32_bf16 v[56:59], v[150:153], v[158:161], v[56:59]
	v_mfma_f32_16x16x32_bf16 v[52:55], v[138:141], v[166:169], v[52:55]
	v_mfma_f32_16x16x32_bf16 v[44:47], v[150:153], v[166:169], v[44:47]
	s_waitcnt lgkmcnt(4)
	v_mfma_f32_16x16x32_bf16 v[36:39], v[138:141], v[188:191], v[36:39]
	v_mfma_f32_16x16x32_bf16 v[28:31], v[150:153], v[188:191], v[28:31]
	v_mfma_f32_16x16x32_bf16 v[20:23], v[138:141], v[196:199], v[20:23]
	v_mfma_f32_16x16x32_bf16 v[12:15], v[150:153], v[196:199], v[12:15]
	s_waitcnt lgkmcnt(2)
	v_mfma_f32_16x16x32_bf16 v[60:63], v[146:149], v[162:165], v[60:63]
	v_mfma_f32_16x16x32_bf16 v[56:59], v[154:157], v[162:165], v[56:59]
	v_mfma_f32_16x16x32_bf16 v[52:55], v[146:149], v[170:173], v[52:55]
	v_mfma_f32_16x16x32_bf16 v[44:47], v[154:157], v[170:173], v[44:47]
	s_waitcnt lgkmcnt(0)
	v_mfma_f32_16x16x32_bf16 v[36:39], v[146:149], v[192:195], v[36:39]
	v_mfma_f32_16x16x32_bf16 v[28:31], v[154:157], v[192:195], v[28:31]
	v_mfma_f32_16x16x32_bf16 v[20:23], v[146:149], v[200:203], v[20:23]
	v_mfma_f32_16x16x32_bf16 v[12:15], v[154:157], v[200:203], v[12:15]
	s_barrier
	s_add_u32 s6, s6, 0x80080
	s_addc_u32 s7, s7, 0
	s_add_i32 s8, s8, s77
	v_lshl_add_u64 v[138:139], s[6:7], 0, v[176:177]
	s_mov_b32 m0, s8
	s_nop 0
	global_load_lds_dwordx4 v[138:139], off
	v_lshl_add_u64 v[138:139], s[6:7], 0, v[132:133]
	s_add_i32 m0, s8, 0x2000
	s_nop 0
	global_load_lds_dwordx4 v[138:139], off
	s_waitcnt vmcnt(6)
	s_barrier
	v_mfma_f32_16x16x32_bf16 v[48:51], v[204:207], v[158:161], v[48:51]
	v_mfma_f32_16x16x32_bf16 v[40:43], v[212:215], v[158:161], v[40:43]
	v_mfma_f32_16x16x32_bf16 v[32:35], v[204:207], v[166:169], v[32:35]
	v_mfma_f32_16x16x32_bf16 v[24:27], v[212:215], v[166:169], v[24:27]
	v_mfma_f32_16x16x32_bf16 v[16:19], v[204:207], v[188:191], v[16:19]
	v_mfma_f32_16x16x32_bf16 v[8:11], v[212:215], v[188:191], v[8:11]
	v_mfma_f32_16x16x32_bf16 v[4:7], v[204:207], v[196:199], v[4:7]
	v_mfma_f32_16x16x32_bf16 v[0:3], v[212:215], v[196:199], v[0:3]
	v_mfma_f32_16x16x32_bf16 v[48:51], v[208:211], v[162:165], v[48:51]
	v_mfma_f32_16x16x32_bf16 v[40:43], v[232:235], v[162:165], v[40:43]
	v_mfma_f32_16x16x32_bf16 v[32:35], v[208:211], v[170:173], v[32:35]
	v_mfma_f32_16x16x32_bf16 v[24:27], v[232:235], v[170:173], v[24:27]
	v_mfma_f32_16x16x32_bf16 v[16:19], v[208:211], v[192:195], v[16:19]
	v_mfma_f32_16x16x32_bf16 v[8:11], v[232:235], v[192:195], v[8:11]
	v_mfma_f32_16x16x32_bf16 v[4:7], v[208:211], v[200:203], v[4:7]
	v_mfma_f32_16x16x32_bf16 v[0:3], v[232:235], v[200:203], v[0:3]
	s_add_i32 s72, s72, 2
	s_add_u32 s4, s4, 0x100
	s_addc_u32 s5, s5, 0
	s_add_u32 s70, s70, 0x100
	s_addc_u32 s71, s71, 0
	s_cmp_lt_u32 s72, 30
	s_barrier
	s_cbranch_scc1 .LBB0_505
	v_mov_b32_e32 v147, v142
	v_mov_b32_e32 v146, v143
	s_cmp_lt_i32 s16, 12
	s_mov_b64 s[4:5], -1
	s_cbranch_scc1 .LBB0_1052
	s_lshl_b32 s4, s18, 8
	s_add_i32 s4, s4, s80
	v_add_u32_e32 v149, s4, v147
	s_lshl_b32 s4, s16, 8
	s_add_i32 s4, s84, s4
	v_lshl_add_u32 v138, v146, 3, s4
	v_mad_i64_i32 v[140:141], s[4:5], v149, s97, 0
	v_cmp_gt_i32_e32 vcc, s34, v138
	s_and_saveexec_b64 s[10:11], vcc
	s_cbranch_execz .LBB0_541
	v_cmp_lt_i32_e64 s[8:9], 63, v138
	v_cmp_gt_u32_e64 s[4:5], s93, v138
	v_cmp_gt_u32_e64 s[6:7], s96, v138
	s_and_saveexec_b64 s[70:71], s[8:9]
	s_xor_b64 s[70:71], exec, s[70:71]
	s_cbranch_execz .LBB0_510
	v_mul_f32_e32 v139, 0xbfb8aa3b, v124
	v_exp_f32_e32 v139, v139
	s_nop 0
	v_add_f32_e32 v139, 1.0, v139
	v_rcp_f32_e32 v139, v139
	s_nop 0
	v_cndmask_b32_e64 v139, 0, v139, s[6:7]
	v_cndmask_b32_e64 v139, v139, v124, s[4:5]
	s_andn2_saveexec_b64 s[70:71], s[70:71]
	s_cbranch_execz .LBB0_512
	s_branch .LBB0_511

.LBB0_1114:
	s_add_i32 vcc_hi, s66, 2
	s_add_u32 s28, s64, 0x80
	s_addc_u32 s29, s65, 0
	s_add_i32 s88, 0, 0x10000
	v_add_u32_e32 v140, s88, v194
	ds_read_b128 v[128:131], v140
	ds_read_b128 v[132:135], v140 offset:1024
	ds_read_b128 v[136:139], v140 offset:2048
	ds_read_b128 v[140:143], v140 offset:3072
	s_cmp_eq_u32 s85, s66
	s_cselect_b32 s66, s4, s28
	s_cselect_b32 s67, s5, s29
	s_cselect_b32 s69, s7, vcc_lo
	s_cselect_b32 s68, s6, s91
	v_lshl_add_u64 v[174:175], s[64:65], 0, v[158:159]
	s_add_i32 m0, s70, 0xc000
	ds_read_b128 v[144:147], v195
	ds_read_b128 v[162:165], v195 offset:2048
	ds_read_b128 v[170:173], v195 offset:4096
	ds_read_b128 v[196:199], v195 offset:6144
	ds_read_b128 v[148:151], v195 offset:1024
	ds_read_b128 v[166:169], v195 offset:3072
	ds_read_b128 v[188:191], v195 offset:5120
	ds_read_b128 v[200:203], v195 offset:7168
	global_load_lds_dwordx4 v[174:175], off
	v_lshl_add_u64 v[174:175], s[64:65], 0, v[160:161]
	s_add_i32 m0, s70, 0xe000
	s_nop 0
	global_load_lds_dwordx4 v[174:175], off
	s_waitcnt lgkmcnt(8)
	s_barrier
	s_waitcnt lgkmcnt(6)
	v_mfma_f32_16x16x32_bf16 v[124:127], v[128:131], v[144:147], v[124:127]
	v_mfma_f32_16x16x32_bf16 v[120:123], v[136:139], v[144:147], v[120:123]
	v_mfma_f32_16x16x32_bf16 v[108:111], v[128:131], v[162:165], v[108:111]
	v_mfma_f32_16x16x32_bf16 v[104:107], v[136:139], v[162:165], v[104:107]
	s_waitcnt lgkmcnt(4)
	v_mfma_f32_16x16x32_bf16 v[92:95], v[128:131], v[170:173], v[92:95]
	v_mfma_f32_16x16x32_bf16 v[88:91], v[136:139], v[170:173], v[88:91]
	v_mfma_f32_16x16x32_bf16 v[76:79], v[128:131], v[196:199], v[76:79]
	v_mfma_f32_16x16x32_bf16 v[72:75], v[136:139], v[196:199], v[72:75]
	s_waitcnt lgkmcnt(2)
	v_mfma_f32_16x16x32_bf16 v[124:127], v[132:135], v[148:151], v[124:127]
	v_mfma_f32_16x16x32_bf16 v[120:123], v[140:143], v[148:151], v[120:123]
	v_mfma_f32_16x16x32_bf16 v[108:111], v[132:135], v[166:169], v[108:111]
	v_mfma_f32_16x16x32_bf16 v[104:107], v[140:143], v[166:169], v[104:107]
	s_waitcnt lgkmcnt(0)
	v_mfma_f32_16x16x32_bf16 v[92:95], v[132:135], v[188:191], v[92:95]
	v_mfma_f32_16x16x32_bf16 v[88:91], v[140:143], v[188:191], v[88:91]
	v_mfma_f32_16x16x32_bf16 v[76:79], v[132:135], v[200:203], v[76:79]
	v_mfma_f32_16x16x32_bf16 v[72:75], v[140:143], v[200:203], v[72:75]
	s_barrier
	s_add_i32 s28, 0, 0x14000
	v_add_u32_e32 v174, s28, v194
	s_add_i32 s29, s88, s47
	ds_read_b128 v[204:207], v174
	ds_read_b128 v[208:211], v174 offset:1024
	ds_read_b128 v[212:215], v174 offset:2048
	ds_read_b128 v[232:235], v174 offset:3072
	v_lshl_add_u64 v[174:175], s[68:69], 0, v[176:177]
	s_mov_b32 m0, s29
	v_lshl_add_u64 v[216:217], s[68:69], 0, v[156:157]
	global_load_lds_dwordx4 v[174:175], off
	s_add_i32 m0, s29, 0x2000
	s_nop 0
	global_load_lds_dwordx4 v[216:217], off
	s_barrier
	s_waitcnt lgkmcnt(1)
	v_mfma_f32_16x16x32_bf16 v[116:119], v[204:207], v[144:147], v[116:119]
	v_mfma_f32_16x16x32_bf16 v[112:115], v[212:215], v[144:147], v[112:115]
	v_mfma_f32_16x16x32_bf16 v[100:103], v[204:207], v[162:165], v[100:103]
	v_mfma_f32_16x16x32_bf16 v[96:99], v[212:215], v[162:165], v[96:99]
	v_mfma_f32_16x16x32_bf16 v[84:87], v[204:207], v[170:173], v[84:87]
	v_mfma_f32_16x16x32_bf16 v[80:83], v[212:215], v[170:173], v[80:83]
	v_mfma_f32_16x16x32_bf16 v[68:71], v[204:207], v[196:199], v[68:71]
	v_mfma_f32_16x16x32_bf16 v[64:67], v[212:215], v[196:199], v[64:67]
	s_waitcnt lgkmcnt(0)
	v_mfma_f32_16x16x32_bf16 v[116:119], v[208:211], v[148:151], v[116:119]
	v_mfma_f32_16x16x32_bf16 v[112:115], v[232:235], v[148:151], v[112:115]
	v_mfma_f32_16x16x32_bf16 v[100:103], v[208:211], v[166:169], v[100:103]
	v_mfma_f32_16x16x32_bf16 v[96:99], v[232:235], v[166:169], v[96:99]
	v_mfma_f32_16x16x32_bf16 v[84:87], v[208:211], v[188:191], v[84:87]
	v_mfma_f32_16x16x32_bf16 v[80:83], v[232:235], v[188:191], v[80:83]
	v_mfma_f32_16x16x32_bf16 v[68:71], v[208:211], v[200:203], v[68:71]
	v_mfma_f32_16x16x32_bf16 v[64:67], v[232:235], v[200:203], v[64:67]
	s_mov_b32 m0, s70
	v_lshl_add_u64 v[236:237], s[66:67], 0, v[152:153]
	s_barrier
	ds_read_b128 v[144:147], v195 offset:16384
	ds_read_b128 v[162:165], v195 offset:18432
	ds_read_b128 v[170:173], v195 offset:20480
	ds_read_b128 v[196:199], v195 offset:22528
	ds_read_b128 v[148:151], v195 offset:17408
	ds_read_b128 v[166:169], v195 offset:19456
	ds_read_b128 v[188:191], v195 offset:21504
	ds_read_b128 v[200:203], v195 offset:23552
	global_load_lds_dwordx4 v[236:237], off
	v_lshl_add_u64 v[238:239], s[66:67], 0, v[154:155]
	s_mov_b32 m0, s71
	s_nop 0
	global_load_lds_dwordx4 v[238:239], off
	s_barrier
	s_waitcnt lgkmcnt(6)
	v_mfma_f32_16x16x32_bf16 v[60:63], v[128:131], v[144:147], v[60:63]
	v_mfma_f32_16x16x32_bf16 v[56:59], v[136:139], v[144:147], v[56:59]
	v_mfma_f32_16x16x32_bf16 v[44:47], v[128:131], v[162:165], v[44:47]
	v_mfma_f32_16x16x32_bf16 v[40:43], v[136:139], v[162:165], v[40:43]
	s_waitcnt lgkmcnt(4)
	v_mfma_f32_16x16x32_bf16 v[28:31], v[128:131], v[170:173], v[28:31]
	v_mfma_f32_16x16x32_bf16 v[24:27], v[136:139], v[170:173], v[24:27]
	v_mfma_f32_16x16x32_bf16 v[12:15], v[128:131], v[196:199], v[12:15]
	v_mfma_f32_16x16x32_bf16 v[8:11], v[136:139], v[196:199], v[8:11]
	s_waitcnt lgkmcnt(2)
	v_mfma_f32_16x16x32_bf16 v[60:63], v[132:135], v[148:151], v[60:63]
	v_mfma_f32_16x16x32_bf16 v[56:59], v[140:143], v[148:151], v[56:59]
	v_mfma_f32_16x16x32_bf16 v[44:47], v[132:135], v[166:169], v[44:47]
	v_mfma_f32_16x16x32_bf16 v[40:43], v[140:143], v[166:169], v[40:43]
	s_waitcnt lgkmcnt(0)
	v_mfma_f32_16x16x32_bf16 v[28:31], v[132:135], v[188:191], v[28:31]
	v_mfma_f32_16x16x32_bf16 v[24:27], v[140:143], v[188:191], v[24:27]
	v_mfma_f32_16x16x32_bf16 v[12:15], v[132:135], v[200:203], v[12:15]
	v_mfma_f32_16x16x32_bf16 v[8:11], v[140:143], v[200:203], v[8:11]
	s_barrier
	s_add_u32 s68, s68, s58
	s_addc_u32 s69, s69, 0
	s_add_i32 s28, s28, s47
	v_lshl_add_u64 v[240:241], s[68:69], 0, v[176:177]
	s_mov_b32 m0, s28
	v_lshl_add_u64 v[242:243], s[68:69], 0, v[156:157]
	global_load_lds_dwordx4 v[240:241], off
	s_add_i32 m0, s28, 0x2000
	s_nop 0
	global_load_lds_dwordx4 v[242:243], off
	s_waitcnt vmcnt(6)
	s_barrier
	v_mfma_f32_16x16x32_bf16 v[52:55], v[204:207], v[144:147], v[52:55]
	v_mfma_f32_16x16x32_bf16 v[48:51], v[212:215], v[144:147], v[48:51]
	v_mfma_f32_16x16x32_bf16 v[36:39], v[204:207], v[162:165], v[36:39]
	v_mfma_f32_16x16x32_bf16 v[32:35], v[212:215], v[162:165], v[32:35]
	v_mfma_f32_16x16x32_bf16 v[20:23], v[204:207], v[170:173], v[20:23]
	v_mfma_f32_16x16x32_bf16 v[16:19], v[212:215], v[170:173], v[16:19]
	v_mfma_f32_16x16x32_bf16 v[4:7], v[204:207], v[196:199], v[4:7]
	v_mfma_f32_16x16x32_bf16 v[0:3], v[212:215], v[196:199], v[0:3]
	v_mfma_f32_16x16x32_bf16 v[52:55], v[208:211], v[148:151], v[52:55]
	v_mfma_f32_16x16x32_bf16 v[48:51], v[232:235], v[148:151], v[48:51]
	v_mfma_f32_16x16x32_bf16 v[36:39], v[208:211], v[166:169], v[36:39]
	v_mfma_f32_16x16x32_bf16 v[32:35], v[232:235], v[166:169], v[32:35]
	v_mfma_f32_16x16x32_bf16 v[20:23], v[208:211], v[188:191], v[20:23]
	v_mfma_f32_16x16x32_bf16 v[16:19], v[232:235], v[188:191], v[16:19]
	v_mfma_f32_16x16x32_bf16 v[4:7], v[208:211], v[200:203], v[4:7]
	v_mfma_f32_16x16x32_bf16 v[0:3], v[232:235], v[200:203], v[0:3]
	s_add_i32 s28, 0, 0x18000
	v_add_u32_e32 v140, s28, v194
	s_barrier
	ds_read_b128 v[128:131], v140
	ds_read_b128 v[132:135], v140 offset:1024
	ds_read_b128 v[136:139], v140 offset:2048
	ds_read_b128 v[140:143], v140 offset:3072
	s_add_u32 s66, s66, s58
	s_addc_u32 s67, s67, 0
	s_mov_b32 m0, s72
	v_lshl_add_u64 v[204:205], s[66:67], 0, v[152:153]
	ds_read_b128 v[144:147], v195 offset:32768
	ds_read_b128 v[162:165], v195 offset:34816
	ds_read_b128 v[170:173], v195 offset:36864
	ds_read_b128 v[196:199], v195 offset:38912
	ds_read_b128 v[148:151], v195 offset:33792
	ds_read_b128 v[166:169], v195 offset:35840
	ds_read_b128 v[188:191], v195 offset:37888
	ds_read_b128 v[200:203], v195 offset:39936
	global_load_lds_dwordx4 v[204:205], off
	v_lshl_add_u64 v[204:205], s[66:67], 0, v[154:155]
	s_mov_b32 m0, s73
	s_nop 0
	global_load_lds_dwordx4 v[204:205], off
	s_waitcnt lgkmcnt(8)
	s_barrier
	s_waitcnt lgkmcnt(6)
	v_mfma_f32_16x16x32_bf16 v[124:127], v[128:131], v[144:147], v[124:127]
	v_mfma_f32_16x16x32_bf16 v[120:123], v[136:139], v[144:147], v[120:123]
	v_mfma_f32_16x16x32_bf16 v[108:111], v[128:131], v[162:165], v[108:111]
	v_mfma_f32_16x16x32_bf16 v[104:107], v[136:139], v[162:165], v[104:107]
	s_waitcnt lgkmcnt(4)
	v_mfma_f32_16x16x32_bf16 v[92:95], v[128:131], v[170:173], v[92:95]
	v_mfma_f32_16x16x32_bf16 v[88:91], v[136:139], v[170:173], v[88:91]
	v_mfma_f32_16x16x32_bf16 v[76:79], v[128:131], v[196:199], v[76:79]
	v_mfma_f32_16x16x32_bf16 v[72:75], v[136:139], v[196:199], v[72:75]
	s_waitcnt lgkmcnt(2)
	v_mfma_f32_16x16x32_bf16 v[124:127], v[132:135], v[148:151], v[124:127]
	v_mfma_f32_16x16x32_bf16 v[120:123], v[140:143], v[148:151], v[120:123]
	v_mfma_f32_16x16x32_bf16 v[108:111], v[132:135], v[166:169], v[108:111]
	v_mfma_f32_16x16x32_bf16 v[104:107], v[140:143], v[166:169], v[104:107]
	s_waitcnt lgkmcnt(0)
	v_mfma_f32_16x16x32_bf16 v[92:95], v[132:135], v[188:191], v[92:95]
	v_mfma_f32_16x16x32_bf16 v[88:91], v[140:143], v[188:191], v[88:91]
	v_mfma_f32_16x16x32_bf16 v[76:79], v[132:135], v[200:203], v[76:79]
	v_mfma_f32_16x16x32_bf16 v[72:75], v[140:143], v[200:203], v[72:75]
	s_barrier
	s_add_i32 s29, 0, 0x1c000
	s_add_i32 s28, s28, s47
	v_add_u32_e32 v232, s29, v194
	v_lshl_add_u64 v[174:175], v[174:175], 0, s[40:41]
	s_mov_b32 m0, s28
	ds_read_b128 v[204:207], v232
	ds_read_b128 v[208:211], v232 offset:1024
	ds_read_b128 v[212:215], v232 offset:2048
	ds_read_b128 v[232:235], v232 offset:3072
	global_load_lds_dwordx4 v[174:175], off
	v_lshl_add_u64 v[174:175], v[216:217], 0, s[40:41]
	s_add_i32 m0, s28, 0x2000
	s_nop 0
	global_load_lds_dwordx4 v[174:175], off
	s_barrier
	s_waitcnt lgkmcnt(1)
	v_mfma_f32_16x16x32_bf16 v[116:119], v[204:207], v[144:147], v[116:119]
	v_mfma_f32_16x16x32_bf16 v[112:115], v[212:215], v[144:147], v[112:115]
	v_mfma_f32_16x16x32_bf16 v[100:103], v[204:207], v[162:165], v[100:103]
	v_mfma_f32_16x16x32_bf16 v[96:99], v[212:215], v[162:165], v[96:99]
	v_mfma_f32_16x16x32_bf16 v[84:87], v[204:207], v[170:173], v[84:87]
	v_mfma_f32_16x16x32_bf16 v[80:83], v[212:215], v[170:173], v[80:83]
	v_mfma_f32_16x16x32_bf16 v[68:71], v[204:207], v[196:199], v[68:71]
	v_mfma_f32_16x16x32_bf16 v[64:67], v[212:215], v[196:199], v[64:67]
	s_waitcnt lgkmcnt(0)
	v_mfma_f32_16x16x32_bf16 v[116:119], v[208:211], v[148:151], v[116:119]
	v_mfma_f32_16x16x32_bf16 v[112:115], v[232:235], v[148:151], v[112:115]
	v_mfma_f32_16x16x32_bf16 v[100:103], v[208:211], v[166:169], v[100:103]
	v_mfma_f32_16x16x32_bf16 v[96:99], v[232:235], v[166:169], v[96:99]
	v_mfma_f32_16x16x32_bf16 v[84:87], v[208:211], v[188:191], v[84:87]
	v_mfma_f32_16x16x32_bf16 v[80:83], v[232:235], v[188:191], v[80:83]
	v_mfma_f32_16x16x32_bf16 v[68:71], v[208:211], v[200:203], v[68:71]
	v_mfma_f32_16x16x32_bf16 v[64:67], v[232:235], v[200:203], v[64:67]
	s_mov_b32 m0, s74
	v_lshl_add_u64 v[174:175], v[236:237], 0, s[40:41]
	s_barrier
	ds_read_b128 v[144:147], v195 offset:49152
	ds_read_b128 v[162:165], v195 offset:51200
	ds_read_b128 v[170:173], v195 offset:53248
	ds_read_b128 v[196:199], v195 offset:55296
	ds_read_b128 v[148:151], v195 offset:50176
	ds_read_b128 v[166:169], v195 offset:52224
	ds_read_b128 v[188:191], v195 offset:54272
	ds_read_b128 v[200:203], v195 offset:56320
	global_load_lds_dwordx4 v[174:175], off
	v_lshl_add_u64 v[174:175], v[238:239], 0, s[40:41]
	s_mov_b32 m0, s75
	s_nop 0
	global_load_lds_dwordx4 v[174:175], off
	s_barrier
	s_waitcnt lgkmcnt(6)
	v_mfma_f32_16x16x32_bf16 v[60:63], v[128:131], v[144:147], v[60:63]
	v_mfma_f32_16x16x32_bf16 v[56:59], v[136:139], v[144:147], v[56:59]
	v_mfma_f32_16x16x32_bf16 v[44:47], v[128:131], v[162:165], v[44:47]
	v_mfma_f32_16x16x32_bf16 v[40:43], v[136:139], v[162:165], v[40:43]
	s_waitcnt lgkmcnt(4)
	v_mfma_f32_16x16x32_bf16 v[28:31], v[128:131], v[170:173], v[28:31]
	v_mfma_f32_16x16x32_bf16 v[24:27], v[136:139], v[170:173], v[24:27]
	v_mfma_f32_16x16x32_bf16 v[12:15], v[128:131], v[196:199], v[12:15]
	v_mfma_f32_16x16x32_bf16 v[8:11], v[136:139], v[196:199], v[8:11]
	s_waitcnt lgkmcnt(2)
	v_mfma_f32_16x16x32_bf16 v[60:63], v[132:135], v[148:151], v[60:63]
	v_mfma_f32_16x16x32_bf16 v[56:59], v[140:143], v[148:151], v[56:59]
	v_mfma_f32_16x16x32_bf16 v[44:47], v[132:135], v[166:169], v[44:47]
	v_mfma_f32_16x16x32_bf16 v[40:43], v[140:143], v[166:169], v[40:43]
	s_waitcnt lgkmcnt(0)
	v_mfma_f32_16x16x32_bf16 v[28:31], v[132:135], v[188:191], v[28:31]
	v_mfma_f32_16x16x32_bf16 v[24:27], v[140:143], v[188:191], v[24:27]
	v_mfma_f32_16x16x32_bf16 v[12:15], v[132:135], v[200:203], v[12:15]
	v_mfma_f32_16x16x32_bf16 v[8:11], v[140:143], v[200:203], v[8:11]
	s_barrier
	s_add_i32 s28, s29, s47
	v_lshl_add_u64 v[128:129], v[240:241], 0, s[40:41]
	s_mov_b32 m0, s28
	s_nop 0
	global_load_lds_dwordx4 v[128:129], off
	v_lshl_add_u64 v[128:129], v[242:243], 0, s[40:41]
	s_add_i32 m0, s28, 0x2000
	s_nop 0
	global_load_lds_dwordx4 v[128:129], off
	s_waitcnt vmcnt(6)
	s_barrier
	v_mfma_f32_16x16x32_bf16 v[52:55], v[204:207], v[144:147], v[52:55]
	v_mfma_f32_16x16x32_bf16 v[48:51], v[212:215], v[144:147], v[48:51]
	v_mfma_f32_16x16x32_bf16 v[36:39], v[204:207], v[162:165], v[36:39]
	v_mfma_f32_16x16x32_bf16 v[32:35], v[212:215], v[162:165], v[32:35]
	v_mfma_f32_16x16x32_bf16 v[20:23], v[204:207], v[170:173], v[20:23]
	v_mfma_f32_16x16x32_bf16 v[16:19], v[212:215], v[170:173], v[16:19]
	v_mfma_f32_16x16x32_bf16 v[4:7], v[204:207], v[196:199], v[4:7]
	v_mfma_f32_16x16x32_bf16 v[0:3], v[212:215], v[196:199], v[0:3]
	v_mfma_f32_16x16x32_bf16 v[52:55], v[208:211], v[148:151], v[52:55]
	v_mfma_f32_16x16x32_bf16 v[48:51], v[232:235], v[148:151], v[48:51]
	v_mfma_f32_16x16x32_bf16 v[36:39], v[208:211], v[166:169], v[36:39]
	v_mfma_f32_16x16x32_bf16 v[32:35], v[232:235], v[166:169], v[32:35]
	v_mfma_f32_16x16x32_bf16 v[20:23], v[208:211], v[188:191], v[20:23]
	v_mfma_f32_16x16x32_bf16 v[16:19], v[232:235], v[188:191], v[16:19]
	v_mfma_f32_16x16x32_bf16 v[4:7], v[208:211], v[200:203], v[4:7]
	v_mfma_f32_16x16x32_bf16 v[0:3], v[232:235], v[200:203], v[0:3]
	s_add_u32 s64, s64, 0x100
	s_addc_u32 s65, s65, 0
	s_add_u32 s91, s91, 0x100
	s_addc_u32 vcc_lo, vcc_lo, 0
	s_cmp_lt_i32 vcc_hi, s76
	s_mov_b32 s66, vcc_hi
	s_barrier
	s_cbranch_scc1 .LBB0_1114
	s_lshl_b32 s28, s84, 8
	v_mov_b32_e32 v128, v193
	v_mov_b32_e32 v129, v192
	s_add_i32 s28, s28, s78
	s_lshl_b32 s64, s24, 2
	v_add_u32_e32 v166, s28, v129
	s_lshl_b32 s28, s24, 8
	s_or_b32 s28, s28, s79
	v_lshl_add_u32 v162, v128, 3, s28
	v_ashrrev_i32_e32 v163, 31, v162
	v_lshlrev_b64 v[204:205], 1, v[162:163]
	v_ashrrev_i32_e32 v167, 31, v166
	v_lshl_add_u64 v[164:165], s[12:13], 0, v[204:205]
	v_lshlrev_b64 v[206:207], 11, v[166:167]
	v_cmp_eq_u32_e32 vcc, 0, v128
	v_lshl_add_u64 v[128:129], v[164:165], 0, v[206:207]
	global_load_dwordx4 v[196:199], v[128:129], off
	global_load_dwordx4 v[200:203], v[128:129], off offset:256
	v_add_u32_e32 v188, 16, v166
	v_ashrrev_i32_e32 v189, 31, v188
	v_add_u32_e32 v172, 32, v166
	v_lshlrev_b64 v[190:191], 11, v[188:189]
	v_ashrrev_i32_e32 v173, 31, v172
	v_add_u32_e32 v168, 48, v166
	v_lshl_add_u64 v[128:129], v[164:165], 0, v[190:191]
	v_lshlrev_b64 v[174:175], 11, v[172:173]
	v_ashrrev_i32_e32 v169, 31, v168
	global_load_dwordx4 v[148:151], v[128:129], off
	global_load_dwordx4 v[144:147], v[128:129], off offset:256
	v_lshl_add_u64 v[128:129], v[164:165], 0, v[174:175]
	v_lshlrev_b64 v[170:171], 11, v[168:169]
	global_load_dwordx4 v[140:143], v[128:129], off
	global_load_dwordx4 v[136:139], v[128:129], off offset:256
	v_lshl_add_u64 v[128:129], v[164:165], 0, v[170:171]
	global_load_dwordx4 v[132:135], v[128:129], off
	s_nop 0
	global_load_dwordx4 v[128:131], v[128:129], off offset:256
	v_lshl_add_u64 v[206:207], s[12:13], 0, v[206:207]
	v_lshl_add_u64 v[204:205], v[206:207], 0, v[204:205]
	s_ashr_i32 s65, s64, 31
	s_waitcnt vmcnt(0)
	v_lshlrev_b32_e32 v208, 16, v196
	v_and_b32_e32 v209, 0xffff0000, v196
	v_lshlrev_b32_e32 v196, 16, v197
	v_and_b32_e32 v197, 0xffff0000, v197
	v_lshlrev_b32_e32 v210, 16, v198
	v_and_b32_e32 v211, 0xffff0000, v198
	v_lshlrev_b32_e32 v198, 16, v199
	v_and_b32_e32 v199, 0xffff0000, v199
	v_pk_fma_f32 v[126:127], s[62:63], v[126:127], v[196:197]
	v_pk_fma_f32 v[124:125], s[10:11], v[124:125], v[208:209]
	v_pk_fma_f32 v[196:197], s[62:63], v[122:123], v[198:199]
	v_pk_fma_f32 v[198:199], s[10:11], v[120:121], v[210:211]
	v_cvt_pk_bf16_f32 v120, v124, v125
	v_cvt_pk_bf16_f32 v121, v126, v127
	s_nop 0
	v_cvt_pk_bf16_f32 v122, v198, v199
	v_cvt_pk_bf16_f32 v123, v196, v197
	global_store_dwordx4 v[204:205], v[120:123], off
	s_nop 1
	v_pk_mul_f32 v[120:121], v[198:199], v[198:199]
	v_pk_mul_f32 v[122:123], v[196:197], v[196:197]
	v_pk_fma_f32 v[120:121], v[124:125], v[124:125], v[120:121]
	v_pk_fma_f32 v[122:123], v[126:127], v[126:127], v[122:123]
	v_add_f32_e32 v120, v120, v121
	v_add_f32_e32 v121, v122, v123
	v_add_f32_e32 v196, v120, v121
	v_lshlrev_b32_e32 v120, 16, v200
	v_and_b32_e32 v121, 0xffff0000, v200
	v_lshlrev_b32_e32 v122, 16, v201
	v_and_b32_e32 v123, 0xffff0000, v201
	v_lshlrev_b32_e32 v124, 16, v202
	v_and_b32_e32 v125, 0xffff0000, v202
	v_lshlrev_b32_e32 v126, 16, v203
	v_and_b32_e32 v127, 0xffff0000, v203
	v_pk_fma_f32 v[118:119], s[62:63], v[118:119], v[122:123]
	v_pk_fma_f32 v[116:117], s[10:11], v[116:117], v[120:121]
	v_pk_fma_f32 v[120:121], s[62:63], v[114:115], v[126:127]
	v_pk_fma_f32 v[122:123], s[10:11], v[112:113], v[124:125]
	v_cvt_pk_bf16_f32 v112, v116, v117
	v_cvt_pk_bf16_f32 v113, v118, v119
	s_nop 0
	v_cvt_pk_bf16_f32 v114, v122, v123
	v_cvt_pk_bf16_f32 v115, v120, v121
	global_store_dwordx4 v[204:205], v[112:115], off offset:256
	s_nop 1
	v_pk_mul_f32 v[112:113], v[122:123], v[122:123]
	v_pk_mul_f32 v[114:115], v[120:121], v[120:121]
	v_pk_fma_f32 v[112:113], v[116:117], v[116:117], v[112:113]
	v_pk_fma_f32 v[114:115], v[118:119], v[118:119], v[114:115]
	v_add_f32_e32 v112, v112, v113
	v_add_f32_e32 v113, v114, v115
	v_add_f32_e32 v112, v112, v113
	v_add_f32_e32 v112, v196, v112
	ds_bpermute_b32 v113, v219, v112
	s_waitcnt lgkmcnt(0)
	v_add_f32_e32 v112, v112, v113
	ds_bpermute_b32 v113, v218, v112
	s_and_saveexec_b64 s[66:67], vcc
	s_cbranch_execz .LBB0_1117
	v_lshlrev_b64 v[114:115], 6, v[166:167]
	v_lshl_add_u64 v[114:115], s[8:9], 0, v[114:115]
	v_lshl_add_u64 v[114:115], s[64:65], 2, v[114:115]
	s_lshl_b32 s24, s77, 2
	v_lshl_add_u64 v[114:115], v[114:115], 0, s[24:25]
	s_waitcnt lgkmcnt(0)
	v_add_f32_e32 v112, v112, v113
	global_store_dword v[114:115], v112, off

.LBB0_1282:
	s_add_i32 s81, s60, 2
	s_add_u32 s28, s58, 0x80
	s_addc_u32 s29, s59, 0
	s_add_i32 s82, 0, 0x10000
	v_add_u32_e32 v140, s82, v195
	ds_read_b128 v[128:131], v140
	ds_read_b128 v[132:135], v140 offset:1024
	ds_read_b128 v[136:139], v140 offset:2048
	ds_read_b128 v[140:143], v140 offset:3072
	s_cmp_eq_u32 s5, s60
	s_cselect_b32 s60, s56, s28
	s_cselect_b32 s61, s57, s29
	s_cselect_b32 s63, s3, s80
	s_cselect_b32 s62, s2, s21
	v_lshl_add_u64 v[174:175], s[58:59], 0, v[158:159]
	s_add_i32 m0, s66, 0xc000
	ds_read_b128 v[144:147], v196
	ds_read_b128 v[162:165], v196 offset:2048
	ds_read_b128 v[170:173], v196 offset:4096
	ds_read_b128 v[198:201], v196 offset:6144
	ds_read_b128 v[148:151], v196 offset:1024
	ds_read_b128 v[166:169], v196 offset:3072
	ds_read_b128 v[188:191], v196 offset:5120
	ds_read_b128 v[202:205], v196 offset:7168
	global_load_lds_dwordx4 v[174:175], off
	v_lshl_add_u64 v[174:175], s[58:59], 0, v[160:161]
	s_add_i32 m0, s66, 0xe000
	s_nop 0
	global_load_lds_dwordx4 v[174:175], off
	s_waitcnt lgkmcnt(8)
	s_barrier
	s_waitcnt lgkmcnt(6)
	v_mfma_f32_16x16x32_bf16 v[124:127], v[128:131], v[144:147], v[124:127]
	v_mfma_f32_16x16x32_bf16 v[120:123], v[136:139], v[144:147], v[120:123]
	v_mfma_f32_16x16x32_bf16 v[108:111], v[128:131], v[162:165], v[108:111]
	v_mfma_f32_16x16x32_bf16 v[104:107], v[136:139], v[162:165], v[104:107]
	s_waitcnt lgkmcnt(4)
	v_mfma_f32_16x16x32_bf16 v[92:95], v[128:131], v[170:173], v[92:95]
	v_mfma_f32_16x16x32_bf16 v[88:91], v[136:139], v[170:173], v[88:91]
	v_mfma_f32_16x16x32_bf16 v[76:79], v[128:131], v[198:201], v[76:79]
	v_mfma_f32_16x16x32_bf16 v[72:75], v[136:139], v[198:201], v[72:75]
	s_waitcnt lgkmcnt(2)
	v_mfma_f32_16x16x32_bf16 v[124:127], v[132:135], v[148:151], v[124:127]
	v_mfma_f32_16x16x32_bf16 v[120:123], v[140:143], v[148:151], v[120:123]
	v_mfma_f32_16x16x32_bf16 v[108:111], v[132:135], v[166:169], v[108:111]
	v_mfma_f32_16x16x32_bf16 v[104:107], v[140:143], v[166:169], v[104:107]
	s_waitcnt lgkmcnt(0)
	v_mfma_f32_16x16x32_bf16 v[92:95], v[132:135], v[188:191], v[92:95]
	v_mfma_f32_16x16x32_bf16 v[88:91], v[140:143], v[188:191], v[88:91]
	v_mfma_f32_16x16x32_bf16 v[76:79], v[132:135], v[202:205], v[76:79]
	v_mfma_f32_16x16x32_bf16 v[72:75], v[140:143], v[202:205], v[72:75]
	s_barrier
	s_add_i32 s28, 0, 0x14000
	v_add_u32_e32 v174, s28, v195
	s_add_i32 s29, s82, s65
	ds_read_b128 v[206:209], v174
	ds_read_b128 v[210:213], v174 offset:1024
	ds_read_b128 v[214:217], v174 offset:2048
	ds_read_b128 v[232:235], v174 offset:3072
	v_lshl_add_u64 v[174:175], s[62:63], 0, v[176:177]
	s_mov_b32 m0, s29
	v_lshl_add_u64 v[236:237], s[62:63], 0, v[156:157]
	global_load_lds_dwordx4 v[174:175], off
	s_add_i32 m0, s29, 0x2000
	s_nop 0
	global_load_lds_dwordx4 v[236:237], off
	s_barrier
	s_waitcnt lgkmcnt(1)
	v_mfma_f32_16x16x32_bf16 v[116:119], v[206:209], v[144:147], v[116:119]
	v_mfma_f32_16x16x32_bf16 v[112:115], v[214:217], v[144:147], v[112:115]
	v_mfma_f32_16x16x32_bf16 v[100:103], v[206:209], v[162:165], v[100:103]
	v_mfma_f32_16x16x32_bf16 v[96:99], v[214:217], v[162:165], v[96:99]
	v_mfma_f32_16x16x32_bf16 v[84:87], v[206:209], v[170:173], v[84:87]
	v_mfma_f32_16x16x32_bf16 v[80:83], v[214:217], v[170:173], v[80:83]
	v_mfma_f32_16x16x32_bf16 v[68:71], v[206:209], v[198:201], v[68:71]
	v_mfma_f32_16x16x32_bf16 v[64:67], v[214:217], v[198:201], v[64:67]
	s_waitcnt lgkmcnt(0)
	v_mfma_f32_16x16x32_bf16 v[116:119], v[210:213], v[148:151], v[116:119]
	v_mfma_f32_16x16x32_bf16 v[112:115], v[232:235], v[148:151], v[112:115]
	v_mfma_f32_16x16x32_bf16 v[100:103], v[210:213], v[166:169], v[100:103]
	v_mfma_f32_16x16x32_bf16 v[96:99], v[232:235], v[166:169], v[96:99]
	v_mfma_f32_16x16x32_bf16 v[84:87], v[210:213], v[188:191], v[84:87]
	v_mfma_f32_16x16x32_bf16 v[80:83], v[232:235], v[188:191], v[80:83]
	v_mfma_f32_16x16x32_bf16 v[68:71], v[210:213], v[202:205], v[68:71]
	v_mfma_f32_16x16x32_bf16 v[64:67], v[232:235], v[202:205], v[64:67]
	s_mov_b32 m0, s66
	v_lshl_add_u64 v[238:239], s[60:61], 0, v[152:153]
	s_barrier
	ds_read_b128 v[144:147], v196 offset:16384
	ds_read_b128 v[162:165], v196 offset:18432
	ds_read_b128 v[170:173], v196 offset:20480
	ds_read_b128 v[198:201], v196 offset:22528
	ds_read_b128 v[148:151], v196 offset:17408
	ds_read_b128 v[166:169], v196 offset:19456
	ds_read_b128 v[188:191], v196 offset:21504
	ds_read_b128 v[202:205], v196 offset:23552
	global_load_lds_dwordx4 v[238:239], off
	v_lshl_add_u64 v[240:241], s[60:61], 0, v[154:155]
	s_mov_b32 m0, s67
	s_nop 0
	global_load_lds_dwordx4 v[240:241], off
	s_barrier
	s_waitcnt lgkmcnt(6)
	v_mfma_f32_16x16x32_bf16 v[60:63], v[128:131], v[144:147], v[60:63]
	v_mfma_f32_16x16x32_bf16 v[56:59], v[136:139], v[144:147], v[56:59]
	v_mfma_f32_16x16x32_bf16 v[44:47], v[128:131], v[162:165], v[44:47]
	v_mfma_f32_16x16x32_bf16 v[40:43], v[136:139], v[162:165], v[40:43]
	s_waitcnt lgkmcnt(4)
	v_mfma_f32_16x16x32_bf16 v[28:31], v[128:131], v[170:173], v[28:31]
	v_mfma_f32_16x16x32_bf16 v[24:27], v[136:139], v[170:173], v[24:27]
	v_mfma_f32_16x16x32_bf16 v[12:15], v[128:131], v[198:201], v[12:15]
	v_mfma_f32_16x16x32_bf16 v[8:11], v[136:139], v[198:201], v[8:11]
	s_waitcnt lgkmcnt(2)
	v_mfma_f32_16x16x32_bf16 v[60:63], v[132:135], v[148:151], v[60:63]
	v_mfma_f32_16x16x32_bf16 v[56:59], v[140:143], v[148:151], v[56:59]
	v_mfma_f32_16x16x32_bf16 v[44:47], v[132:135], v[166:169], v[44:47]
	v_mfma_f32_16x16x32_bf16 v[40:43], v[140:143], v[166:169], v[40:43]
	s_waitcnt lgkmcnt(0)
	v_mfma_f32_16x16x32_bf16 v[28:31], v[132:135], v[188:191], v[28:31]
	v_mfma_f32_16x16x32_bf16 v[24:27], v[140:143], v[188:191], v[24:27]
	v_mfma_f32_16x16x32_bf16 v[12:15], v[132:135], v[202:205], v[12:15]
	v_mfma_f32_16x16x32_bf16 v[8:11], v[140:143], v[202:205], v[8:11]
	s_barrier
	s_add_u32 s62, s62, s4
	s_addc_u32 s63, s63, 0
	s_add_i32 s28, s28, s65
	v_lshl_add_u64 v[242:243], s[62:63], 0, v[176:177]
	s_mov_b32 m0, s28
	v_lshl_add_u64 v[244:245], s[62:63], 0, v[156:157]
	global_load_lds_dwordx4 v[242:243], off
	s_add_i32 m0, s28, 0x2000
	s_nop 0
	global_load_lds_dwordx4 v[244:245], off
	s_waitcnt vmcnt(6)
	s_barrier
	v_mfma_f32_16x16x32_bf16 v[52:55], v[206:209], v[144:147], v[52:55]
	v_mfma_f32_16x16x32_bf16 v[48:51], v[214:217], v[144:147], v[48:51]
	v_mfma_f32_16x16x32_bf16 v[36:39], v[206:209], v[162:165], v[36:39]
	v_mfma_f32_16x16x32_bf16 v[32:35], v[214:217], v[162:165], v[32:35]
	v_mfma_f32_16x16x32_bf16 v[20:23], v[206:209], v[170:173], v[20:23]
	v_mfma_f32_16x16x32_bf16 v[16:19], v[214:217], v[170:173], v[16:19]
	v_mfma_f32_16x16x32_bf16 v[4:7], v[206:209], v[198:201], v[4:7]
	v_mfma_f32_16x16x32_bf16 v[0:3], v[214:217], v[198:201], v[0:3]
	v_mfma_f32_16x16x32_bf16 v[52:55], v[210:213], v[148:151], v[52:55]
	v_mfma_f32_16x16x32_bf16 v[48:51], v[232:235], v[148:151], v[48:51]
	v_mfma_f32_16x16x32_bf16 v[36:39], v[210:213], v[166:169], v[36:39]
	v_mfma_f32_16x16x32_bf16 v[32:35], v[232:235], v[166:169], v[32:35]
	v_mfma_f32_16x16x32_bf16 v[20:23], v[210:213], v[188:191], v[20:23]
	v_mfma_f32_16x16x32_bf16 v[16:19], v[232:235], v[188:191], v[16:19]
	v_mfma_f32_16x16x32_bf16 v[4:7], v[210:213], v[202:205], v[4:7]
	v_mfma_f32_16x16x32_bf16 v[0:3], v[232:235], v[202:205], v[0:3]
	s_add_i32 s28, 0, 0x18000
	v_add_u32_e32 v140, s28, v195
	s_barrier
	ds_read_b128 v[128:131], v140
	ds_read_b128 v[132:135], v140 offset:1024
	ds_read_b128 v[136:139], v140 offset:2048
	ds_read_b128 v[140:143], v140 offset:3072
	s_add_u32 s60, s60, s4
	s_addc_u32 s61, s61, 0
	s_mov_b32 m0, s68
	v_lshl_add_u64 v[206:207], s[60:61], 0, v[152:153]
	ds_read_b128 v[144:147], v196 offset:32768
	ds_read_b128 v[162:165], v196 offset:34816
	ds_read_b128 v[170:173], v196 offset:36864
	ds_read_b128 v[198:201], v196 offset:38912
	ds_read_b128 v[148:151], v196 offset:33792
	ds_read_b128 v[166:169], v196 offset:35840
	ds_read_b128 v[188:191], v196 offset:37888
	ds_read_b128 v[202:205], v196 offset:39936
	global_load_lds_dwordx4 v[206:207], off
	v_lshl_add_u64 v[206:207], s[60:61], 0, v[154:155]
	s_mov_b32 m0, s69
	s_nop 0
	global_load_lds_dwordx4 v[206:207], off
	s_waitcnt lgkmcnt(8)
	s_barrier
	s_waitcnt lgkmcnt(6)
	v_mfma_f32_16x16x32_bf16 v[124:127], v[128:131], v[144:147], v[124:127]
	v_mfma_f32_16x16x32_bf16 v[120:123], v[136:139], v[144:147], v[120:123]
	v_mfma_f32_16x16x32_bf16 v[108:111], v[128:131], v[162:165], v[108:111]
	v_mfma_f32_16x16x32_bf16 v[104:107], v[136:139], v[162:165], v[104:107]
	s_waitcnt lgkmcnt(4)
	v_mfma_f32_16x16x32_bf16 v[92:95], v[128:131], v[170:173], v[92:95]
	v_mfma_f32_16x16x32_bf16 v[88:91], v[136:139], v[170:173], v[88:91]
	v_mfma_f32_16x16x32_bf16 v[76:79], v[128:131], v[198:201], v[76:79]
	v_mfma_f32_16x16x32_bf16 v[72:75], v[136:139], v[198:201], v[72:75]
	s_waitcnt lgkmcnt(2)
	v_mfma_f32_16x16x32_bf16 v[124:127], v[132:135], v[148:151], v[124:127]
	v_mfma_f32_16x16x32_bf16 v[120:123], v[140:143], v[148:151], v[120:123]
	v_mfma_f32_16x16x32_bf16 v[108:111], v[132:135], v[166:169], v[108:111]
	v_mfma_f32_16x16x32_bf16 v[104:107], v[140:143], v[166:169], v[104:107]
	s_waitcnt lgkmcnt(0)
	v_mfma_f32_16x16x32_bf16 v[92:95], v[132:135], v[188:191], v[92:95]
	v_mfma_f32_16x16x32_bf16 v[88:91], v[140:143], v[188:191], v[88:91]
	v_mfma_f32_16x16x32_bf16 v[76:79], v[132:135], v[202:205], v[76:79]
	v_mfma_f32_16x16x32_bf16 v[72:75], v[140:143], v[202:205], v[72:75]
	s_barrier
	s_add_i32 s29, 0, 0x1c000
	s_add_i32 s28, s28, s65
	v_add_u32_e32 v197, s29, v195
	v_lshl_add_u64 v[174:175], v[174:175], 0, s[40:41]
	s_mov_b32 m0, s28
	ds_read_b128 v[206:209], v197
	ds_read_b128 v[210:213], v197 offset:1024
	ds_read_b128 v[214:217], v197 offset:2048
	ds_read_b128 v[232:235], v197 offset:3072
	global_load_lds_dwordx4 v[174:175], off
	v_lshl_add_u64 v[174:175], v[236:237], 0, s[40:41]
	s_add_i32 m0, s28, 0x2000
	s_nop 0
	global_load_lds_dwordx4 v[174:175], off
	s_barrier
	s_waitcnt lgkmcnt(1)
	v_mfma_f32_16x16x32_bf16 v[116:119], v[206:209], v[144:147], v[116:119]
	v_mfma_f32_16x16x32_bf16 v[112:115], v[214:217], v[144:147], v[112:115]
	v_mfma_f32_16x16x32_bf16 v[100:103], v[206:209], v[162:165], v[100:103]
	v_mfma_f32_16x16x32_bf16 v[96:99], v[214:217], v[162:165], v[96:99]
	v_mfma_f32_16x16x32_bf16 v[84:87], v[206:209], v[170:173], v[84:87]
	v_mfma_f32_16x16x32_bf16 v[80:83], v[214:217], v[170:173], v[80:83]
	v_mfma_f32_16x16x32_bf16 v[68:71], v[206:209], v[198:201], v[68:71]
	v_mfma_f32_16x16x32_bf16 v[64:67], v[214:217], v[198:201], v[64:67]
	s_waitcnt lgkmcnt(0)
	v_mfma_f32_16x16x32_bf16 v[116:119], v[210:213], v[148:151], v[116:119]
	v_mfma_f32_16x16x32_bf16 v[112:115], v[232:235], v[148:151], v[112:115]
	v_mfma_f32_16x16x32_bf16 v[100:103], v[210:213], v[166:169], v[100:103]
	v_mfma_f32_16x16x32_bf16 v[96:99], v[232:235], v[166:169], v[96:99]
	v_mfma_f32_16x16x32_bf16 v[84:87], v[210:213], v[188:191], v[84:87]
	v_mfma_f32_16x16x32_bf16 v[80:83], v[232:235], v[188:191], v[80:83]
	v_mfma_f32_16x16x32_bf16 v[68:71], v[210:213], v[202:205], v[68:71]
	v_mfma_f32_16x16x32_bf16 v[64:67], v[232:235], v[202:205], v[64:67]
	s_mov_b32 m0, s71
	v_lshl_add_u64 v[174:175], v[238:239], 0, s[40:41]
	s_barrier
	ds_read_b128 v[144:147], v196 offset:49152
	ds_read_b128 v[162:165], v196 offset:51200
	ds_read_b128 v[170:173], v196 offset:53248
	ds_read_b128 v[198:201], v196 offset:55296
	ds_read_b128 v[148:151], v196 offset:50176
	ds_read_b128 v[166:169], v196 offset:52224
	ds_read_b128 v[188:191], v196 offset:54272
	ds_read_b128 v[202:205], v196 offset:56320
	global_load_lds_dwordx4 v[174:175], off
	v_lshl_add_u64 v[174:175], v[240:241], 0, s[40:41]
	s_mov_b32 m0, s72
	s_nop 0
	global_load_lds_dwordx4 v[174:175], off
	s_barrier
	s_waitcnt lgkmcnt(6)
	v_mfma_f32_16x16x32_bf16 v[60:63], v[128:131], v[144:147], v[60:63]
	v_mfma_f32_16x16x32_bf16 v[56:59], v[136:139], v[144:147], v[56:59]
	v_mfma_f32_16x16x32_bf16 v[44:47], v[128:131], v[162:165], v[44:47]
	v_mfma_f32_16x16x32_bf16 v[40:43], v[136:139], v[162:165], v[40:43]
	s_waitcnt lgkmcnt(4)
	v_mfma_f32_16x16x32_bf16 v[28:31], v[128:131], v[170:173], v[28:31]
	v_mfma_f32_16x16x32_bf16 v[24:27], v[136:139], v[170:173], v[24:27]
	v_mfma_f32_16x16x32_bf16 v[12:15], v[128:131], v[198:201], v[12:15]
	v_mfma_f32_16x16x32_bf16 v[8:11], v[136:139], v[198:201], v[8:11]
	s_waitcnt lgkmcnt(2)
	v_mfma_f32_16x16x32_bf16 v[60:63], v[132:135], v[148:151], v[60:63]
	v_mfma_f32_16x16x32_bf16 v[56:59], v[140:143], v[148:151], v[56:59]
	v_mfma_f32_16x16x32_bf16 v[44:47], v[132:135], v[166:169], v[44:47]
	v_mfma_f32_16x16x32_bf16 v[40:43], v[140:143], v[166:169], v[40:43]
	s_waitcnt lgkmcnt(0)
	v_mfma_f32_16x16x32_bf16 v[28:31], v[132:135], v[188:191], v[28:31]
	v_mfma_f32_16x16x32_bf16 v[24:27], v[140:143], v[188:191], v[24:27]
	v_mfma_f32_16x16x32_bf16 v[12:15], v[132:135], v[202:205], v[12:15]
	v_mfma_f32_16x16x32_bf16 v[8:11], v[140:143], v[202:205], v[8:11]
	s_barrier
	s_add_i32 s28, s29, s65
	v_lshl_add_u64 v[128:129], v[242:243], 0, s[40:41]
	s_mov_b32 m0, s28
	s_nop 0
	global_load_lds_dwordx4 v[128:129], off
	v_lshl_add_u64 v[128:129], v[244:245], 0, s[40:41]
	s_add_i32 m0, s28, 0x2000
	s_nop 0
	global_load_lds_dwordx4 v[128:129], off
	s_waitcnt vmcnt(6)
	s_barrier
	v_mfma_f32_16x16x32_bf16 v[52:55], v[206:209], v[144:147], v[52:55]
	v_mfma_f32_16x16x32_bf16 v[48:51], v[214:217], v[144:147], v[48:51]
	v_mfma_f32_16x16x32_bf16 v[36:39], v[206:209], v[162:165], v[36:39]
	v_mfma_f32_16x16x32_bf16 v[32:35], v[214:217], v[162:165], v[32:35]
	v_mfma_f32_16x16x32_bf16 v[20:23], v[206:209], v[170:173], v[20:23]
	v_mfma_f32_16x16x32_bf16 v[16:19], v[214:217], v[170:173], v[16:19]
	v_mfma_f32_16x16x32_bf16 v[4:7], v[206:209], v[198:201], v[4:7]
	v_mfma_f32_16x16x32_bf16 v[0:3], v[214:217], v[198:201], v[0:3]
	v_mfma_f32_16x16x32_bf16 v[52:55], v[210:213], v[148:151], v[52:55]
	v_mfma_f32_16x16x32_bf16 v[48:51], v[232:235], v[148:151], v[48:51]
	v_mfma_f32_16x16x32_bf16 v[36:39], v[210:213], v[166:169], v[36:39]
	v_mfma_f32_16x16x32_bf16 v[32:35], v[232:235], v[166:169], v[32:35]
	v_mfma_f32_16x16x32_bf16 v[20:23], v[210:213], v[188:191], v[20:23]
	v_mfma_f32_16x16x32_bf16 v[16:19], v[232:235], v[188:191], v[16:19]
	v_mfma_f32_16x16x32_bf16 v[4:7], v[210:213], v[202:205], v[4:7]
	v_mfma_f32_16x16x32_bf16 v[0:3], v[232:235], v[202:205], v[0:3]
	s_add_u32 s58, s58, 0x100
	s_addc_u32 s59, s59, 0
	s_add_u32 s21, s21, 0x100
	s_addc_u32 s80, s80, 0
	s_cmp_ge_i32 s81, s79
	s_mov_b32 s60, s81
	s_barrier
	s_cbranch_scc0 .LBB0_1282
	s_cmp_gt_i32 s24, -1
	s_mov_b64 s[58:59], -1
	s_cbranch_scc0 .LBB0_1285
	s_lshl_b64 s[58:59], s[24:25], 17
	v_mov_b32_e32 v128, v231
	s_add_u32 s58, s37, s58
	s_addc_u32 s59, s46, s59
	v_ashrrev_i32_e32 v129, 31, v128
	v_lshl_add_u64 v[128:129], v[128:129], 4, s[58:59]
	v_add_co_u32_e32 v134, vcc, s36, v128
	v_cvt_pk_bf16_f32 v130, v124, v125
	v_cvt_pk_bf16_f32 v131, v126, v127
	v_cvt_pk_bf16_f32 v132, v120, v121
	v_cvt_pk_bf16_f32 v133, v122, v123
	s_nop 1
	v_addc_co_u32_e32 v135, vcc, 0, v129, vcc
	s_movk_i32 s5, 0x4000
	global_store_dwordx4 v[128:129], v[130:133], off
	s_mov_b64 s[58:59], 0
	s_nop 0
	v_cvt_pk_bf16_f32 v130, v108, v109
	v_cvt_pk_bf16_f32 v131, v110, v111
	v_cvt_pk_bf16_f32 v132, v104, v105
	v_cvt_pk_bf16_f32 v133, v106, v107
	global_store_dwordx4 v[134:135], v[130:133], off
	v_add_co_u32_e32 v134, vcc, s5, v128
	s_movk_i32 s5, 0x6000
	s_nop 0
	v_addc_co_u32_e32 v135, vcc, 0, v129, vcc
	v_cvt_pk_bf16_f32 v130, v92, v93
	v_cvt_pk_bf16_f32 v131, v94, v95
	v_cvt_pk_bf16_f32 v132, v88, v89
	v_cvt_pk_bf16_f32 v133, v90, v91
	global_store_dwordx4 v[134:135], v[130:133], off
	v_add_co_u32_e32 v134, vcc, s5, v128
	s_nop 0
	v_cvt_pk_bf16_f32 v130, v76, v77
	v_cvt_pk_bf16_f32 v131, v78, v79
	v_cvt_pk_bf16_f32 v132, v72, v73
	v_cvt_pk_bf16_f32 v133, v74, v75
	s_nop 0
	v_addc_co_u32_e32 v135, vcc, 0, v129, vcc
	global_store_dwordx4 v[134:135], v[130:133], off
	v_add_co_u32_e32 v134, vcc, s92, v128
	s_mov_b32 s5, 0xa000
	s_nop 0
	v_addc_co_u32_e32 v135, vcc, 0, v129, vcc
	v_cvt_pk_bf16_f32 v130, v116, v117
	v_cvt_pk_bf16_f32 v131, v118, v119
	v_cvt_pk_bf16_f32 v132, v112, v113
	v_cvt_pk_bf16_f32 v133, v114, v115
	global_store_dwordx4 v[134:135], v[130:133], off
	v_add_co_u32_e32 v134, vcc, s5, v128
	s_mov_b32 s5, 0xc000
	s_nop 0
	v_addc_co_u32_e32 v135, vcc, 0, v129, vcc
	v_cvt_pk_bf16_f32 v130, v100, v101
	v_cvt_pk_bf16_f32 v131, v102, v103
	v_cvt_pk_bf16_f32 v132, v96, v97
	v_cvt_pk_bf16_f32 v133, v98, v99
	global_store_dwordx4 v[134:135], v[130:133], off
	v_add_co_u32_e32 v134, vcc, s5, v128
	s_mov_b32 s5, 0xe000
	s_nop 0
	v_addc_co_u32_e32 v135, vcc, 0, v129, vcc
	v_cvt_pk_bf16_f32 v130, v84, v85
	v_cvt_pk_bf16_f32 v131, v86, v87
	v_cvt_pk_bf16_f32 v132, v80, v81
	v_cvt_pk_bf16_f32 v133, v82, v83
	global_store_dwordx4 v[134:135], v[130:133], off
	v_add_co_u32_e32 v134, vcc, s5, v128
	s_mov_b32 s5, 0x10000
	s_nop 0
	v_addc_co_u32_e32 v135, vcc, 0, v129, vcc
	v_cvt_pk_bf16_f32 v130, v68, v69
	v_cvt_pk_bf16_f32 v131, v70, v71
	v_cvt_pk_bf16_f32 v132, v64, v65
	v_cvt_pk_bf16_f32 v133, v66, v67
	global_store_dwordx4 v[134:135], v[130:133], off
	v_add_co_u32_e32 v134, vcc, s5, v128
	s_mov_b32 s5, 0x12000
	s_nop 0
	v_addc_co_u32_e32 v135, vcc, 0, v129, vcc
	v_cvt_pk_bf16_f32 v130, v60, v61
	v_cvt_pk_bf16_f32 v131, v62, v63
	v_cvt_pk_bf16_f32 v132, v56, v57
	v_cvt_pk_bf16_f32 v133, v58, v59
	global_store_dwordx4 v[134:135], v[130:133], off
	v_add_co_u32_e32 v134, vcc, s5, v128
	s_mov_b32 s5, 0x14000
	s_nop 0
	v_addc_co_u32_e32 v135, vcc, 0, v129, vcc
	v_cvt_pk_bf16_f32 v130, v44, v45
	v_cvt_pk_bf16_f32 v131, v46, v47
	v_cvt_pk_bf16_f32 v132, v40, v41
	v_cvt_pk_bf16_f32 v133, v42, v43
	global_store_dwordx4 v[134:135], v[130:133], off
	v_add_co_u32_e32 v134, vcc, s5, v128
	s_mov_b32 s5, 0x16000
	s_nop 0
	v_addc_co_u32_e32 v135, vcc, 0, v129, vcc
	v_cvt_pk_bf16_f32 v130, v28, v29
	v_cvt_pk_bf16_f32 v131, v30, v31
	v_cvt_pk_bf16_f32 v132, v24, v25
	v_cvt_pk_bf16_f32 v133, v26, v27
	global_store_dwordx4 v[134:135], v[130:133], off
	v_add_co_u32_e32 v134, vcc, s5, v128
	s_mov_b32 s5, 0x18000
	s_nop 0
	v_addc_co_u32_e32 v135, vcc, 0, v129, vcc
	v_cvt_pk_bf16_f32 v130, v12, v13
	v_cvt_pk_bf16_f32 v131, v14, v15
	v_cvt_pk_bf16_f32 v132, v8, v9
	v_cvt_pk_bf16_f32 v133, v10, v11
	global_store_dwordx4 v[134:135], v[130:133], off
	v_add_co_u32_e32 v134, vcc, s5, v128
	s_mov_b32 s5, 0x1a000
	s_nop 0
	v_addc_co_u32_e32 v135, vcc, 0, v129, vcc
	v_cvt_pk_bf16_f32 v130, v52, v53
	v_cvt_pk_bf16_f32 v131, v54, v55
	v_cvt_pk_bf16_f32 v132, v48, v49
	v_cvt_pk_bf16_f32 v133, v50, v51
	global_store_dwordx4 v[134:135], v[130:133], off
	v_add_co_u32_e32 v134, vcc, s5, v128
	s_mov_b32 s5, 0x1c000
	s_nop 0
	v_addc_co_u32_e32 v135, vcc, 0, v129, vcc
	v_cvt_pk_bf16_f32 v130, v36, v37
	v_cvt_pk_bf16_f32 v131, v38, v39
	v_cvt_pk_bf16_f32 v132, v32, v33
	v_cvt_pk_bf16_f32 v133, v34, v35
	global_store_dwordx4 v[134:135], v[130:133], off
	v_add_co_u32_e32 v134, vcc, s5, v128
	s_nop 0
	v_cvt_pk_bf16_f32 v130, v20, v21
	v_cvt_pk_bf16_f32 v131, v22, v23
	v_cvt_pk_bf16_f32 v132, v16, v17
	v_cvt_pk_bf16_f32 v133, v18, v19
	s_nop 0
	v_addc_co_u32_e32 v135, vcc, 0, v129, vcc
	v_add_co_u32_e32 v128, vcc, 0x1e000, v128
	global_store_dwordx4 v[134:135], v[130:133], off
	s_nop 0
	v_addc_co_u32_e32 v129, vcc, 0, v129, vcc
	v_cvt_pk_bf16_f32 v130, v4, v5
	v_cvt_pk_bf16_f32 v131, v6, v7
	v_cvt_pk_bf16_f32 v132, v0, v1
	v_cvt_pk_bf16_f32 v133, v2, v3
	global_store_dwordx4 v[128:129], v[130:133], off

.LBB0_1436:
	s_add_u32 s28, s6, 0xfffc0080
	s_addc_u32 s29, s7, -1
	s_add_i32 s71, 0, 0x10000
	v_add_u32_e32 v140, s71, v200
	ds_read_b128 v[128:131], v140
	ds_read_b128 v[132:135], v140 offset:1024
	ds_read_b128 v[136:139], v140 offset:2048
	ds_read_b128 v[140:143], v140 offset:3072
	s_cmp_eq_u32 s70, 12
	s_cselect_b32 s53, s17, s29
	s_cselect_b32 s52, s66, s28
	s_cselect_b32 s51, s13, s69
	s_cselect_b32 s50, s67, s68
	v_lshl_add_u64 v[174:175], s[6:7], 0, v[162:163]
	s_add_i32 m0, s56, 0xc000
	ds_read_b128 v[144:147], v201
	ds_read_b128 v[152:155], v201 offset:2048
	ds_read_b128 v[170:173], v201 offset:4096
	ds_read_b128 v[192:195], v201 offset:6144
	ds_read_b128 v[148:151], v201 offset:1024
	ds_read_b128 v[166:169], v201 offset:3072
	ds_read_b128 v[188:191], v201 offset:5120
	ds_read_b128 v[202:205], v201 offset:7168
	global_load_lds_dwordx4 v[174:175], off
	v_lshl_add_u64 v[174:175], s[6:7], 0, v[164:165]
	s_add_i32 m0, s56, 0xe000
	s_nop 0
	global_load_lds_dwordx4 v[174:175], off
	s_waitcnt lgkmcnt(8)
	s_barrier
	s_waitcnt lgkmcnt(6)
	v_mfma_f32_16x16x32_bf16 v[124:127], v[128:131], v[144:147], v[124:127]
	v_mfma_f32_16x16x32_bf16 v[116:119], v[136:139], v[144:147], v[116:119]
	v_mfma_f32_16x16x32_bf16 v[108:111], v[128:131], v[152:155], v[108:111]
	v_mfma_f32_16x16x32_bf16 v[100:103], v[136:139], v[152:155], v[100:103]
	s_waitcnt lgkmcnt(4)
	v_mfma_f32_16x16x32_bf16 v[92:95], v[128:131], v[170:173], v[92:95]
	v_mfma_f32_16x16x32_bf16 v[84:87], v[136:139], v[170:173], v[84:87]
	v_mfma_f32_16x16x32_bf16 v[76:79], v[128:131], v[192:195], v[76:79]
	v_mfma_f32_16x16x32_bf16 v[68:71], v[136:139], v[192:195], v[68:71]
	s_waitcnt lgkmcnt(2)
	v_mfma_f32_16x16x32_bf16 v[124:127], v[132:135], v[148:151], v[124:127]
	v_mfma_f32_16x16x32_bf16 v[116:119], v[140:143], v[148:151], v[116:119]
	v_mfma_f32_16x16x32_bf16 v[108:111], v[132:135], v[166:169], v[108:111]
	v_mfma_f32_16x16x32_bf16 v[100:103], v[140:143], v[166:169], v[100:103]
	s_waitcnt lgkmcnt(0)
	v_mfma_f32_16x16x32_bf16 v[92:95], v[132:135], v[188:191], v[92:95]
	v_mfma_f32_16x16x32_bf16 v[84:87], v[140:143], v[188:191], v[84:87]
	v_mfma_f32_16x16x32_bf16 v[76:79], v[132:135], v[202:205], v[76:79]
	v_mfma_f32_16x16x32_bf16 v[68:71], v[140:143], v[202:205], v[68:71]
	s_barrier
	s_add_i32 s28, 0, 0x14000
	v_add_u32_e32 v174, s28, v200
	s_add_i32 s29, s71, s55
	ds_read_b128 v[206:209], v174
	ds_read_b128 v[210:213], v174 offset:1024
	ds_read_b128 v[214:217], v174 offset:2048
	ds_read_b128 v[232:235], v174 offset:3072
	v_lshl_add_u64 v[174:175], s[50:51], 0, v[176:177]
	s_mov_b32 m0, s29
	v_lshl_add_u64 v[196:197], s[50:51], 0, v[160:161]
	global_load_lds_dwordx4 v[174:175], off
	s_add_i32 m0, s29, 0x2000
	s_nop 0
	global_load_lds_dwordx4 v[196:197], off
	s_barrier
	s_waitcnt lgkmcnt(1)
	v_mfma_f32_16x16x32_bf16 v[120:123], v[206:209], v[144:147], v[120:123]
	v_mfma_f32_16x16x32_bf16 v[112:115], v[214:217], v[144:147], v[112:115]
	v_mfma_f32_16x16x32_bf16 v[104:107], v[206:209], v[152:155], v[104:107]
	v_mfma_f32_16x16x32_bf16 v[96:99], v[214:217], v[152:155], v[96:99]
	v_mfma_f32_16x16x32_bf16 v[88:91], v[206:209], v[170:173], v[88:91]
	v_mfma_f32_16x16x32_bf16 v[80:83], v[214:217], v[170:173], v[80:83]
	v_mfma_f32_16x16x32_bf16 v[72:75], v[206:209], v[192:195], v[72:75]
	v_mfma_f32_16x16x32_bf16 v[64:67], v[214:217], v[192:195], v[64:67]
	s_waitcnt lgkmcnt(0)
	v_mfma_f32_16x16x32_bf16 v[120:123], v[210:213], v[148:151], v[120:123]
	v_mfma_f32_16x16x32_bf16 v[112:115], v[232:235], v[148:151], v[112:115]
	v_mfma_f32_16x16x32_bf16 v[104:107], v[210:213], v[166:169], v[104:107]
	v_mfma_f32_16x16x32_bf16 v[96:99], v[232:235], v[166:169], v[96:99]
	v_mfma_f32_16x16x32_bf16 v[88:91], v[210:213], v[188:191], v[88:91]
	v_mfma_f32_16x16x32_bf16 v[80:83], v[232:235], v[188:191], v[80:83]
	v_mfma_f32_16x16x32_bf16 v[72:75], v[210:213], v[202:205], v[72:75]
	v_mfma_f32_16x16x32_bf16 v[64:67], v[232:235], v[202:205], v[64:67]
	s_mov_b32 m0, s56
	v_lshl_add_u64 v[236:237], s[52:53], 0, v[156:157]
	s_barrier
	ds_read_b128 v[144:147], v201 offset:16384
	ds_read_b128 v[152:155], v201 offset:18432
	ds_read_b128 v[170:173], v201 offset:20480
	ds_read_b128 v[192:195], v201 offset:22528
	ds_read_b128 v[148:151], v201 offset:17408
	ds_read_b128 v[166:169], v201 offset:19456
	ds_read_b128 v[188:191], v201 offset:21504
	ds_read_b128 v[202:205], v201 offset:23552
	global_load_lds_dwordx4 v[236:237], off
	v_lshl_add_u64 v[238:239], s[52:53], 0, v[158:159]
	s_mov_b32 m0, s57
	s_nop 0
	global_load_lds_dwordx4 v[238:239], off
	s_barrier
	s_waitcnt lgkmcnt(6)
	v_mfma_f32_16x16x32_bf16 v[60:63], v[128:131], v[144:147], v[60:63]
	v_mfma_f32_16x16x32_bf16 v[52:55], v[136:139], v[144:147], v[52:55]
	v_mfma_f32_16x16x32_bf16 v[44:47], v[128:131], v[152:155], v[44:47]
	v_mfma_f32_16x16x32_bf16 v[36:39], v[136:139], v[152:155], v[36:39]
	s_waitcnt lgkmcnt(4)
	v_mfma_f32_16x16x32_bf16 v[28:31], v[128:131], v[170:173], v[28:31]
	v_mfma_f32_16x16x32_bf16 v[20:23], v[136:139], v[170:173], v[20:23]
	v_mfma_f32_16x16x32_bf16 v[12:15], v[128:131], v[192:195], v[12:15]
	v_mfma_f32_16x16x32_bf16 v[4:7], v[136:139], v[192:195], v[4:7]
	s_waitcnt lgkmcnt(2)
	v_mfma_f32_16x16x32_bf16 v[60:63], v[132:135], v[148:151], v[60:63]
	v_mfma_f32_16x16x32_bf16 v[52:55], v[140:143], v[148:151], v[52:55]
	v_mfma_f32_16x16x32_bf16 v[44:47], v[132:135], v[166:169], v[44:47]
	v_mfma_f32_16x16x32_bf16 v[36:39], v[140:143], v[166:169], v[36:39]
	s_waitcnt lgkmcnt(0)
	v_mfma_f32_16x16x32_bf16 v[28:31], v[132:135], v[188:191], v[28:31]
	v_mfma_f32_16x16x32_bf16 v[20:23], v[140:143], v[188:191], v[20:23]
	v_mfma_f32_16x16x32_bf16 v[12:15], v[132:135], v[202:205], v[12:15]
	v_mfma_f32_16x16x32_bf16 v[4:7], v[140:143], v[202:205], v[4:7]
	s_barrier
	s_add_u32 s72, s50, 0x40000
	s_addc_u32 s73, s51, 0
	s_add_i32 s28, s28, s55
	v_lshl_add_u64 v[128:129], s[72:73], 0, v[176:177]
	s_mov_b32 m0, s28
	s_nop 0
	global_load_lds_dwordx4 v[128:129], off
	v_lshl_add_u64 v[128:129], s[72:73], 0, v[160:161]
	s_add_i32 m0, s28, 0x2000
	s_nop 0
	global_load_lds_dwordx4 v[128:129], off
	s_waitcnt vmcnt(6)
	s_barrier
	v_mfma_f32_16x16x32_bf16 v[56:59], v[206:209], v[144:147], v[56:59]
	v_mfma_f32_16x16x32_bf16 v[48:51], v[214:217], v[144:147], v[48:51]
	v_mfma_f32_16x16x32_bf16 v[40:43], v[206:209], v[152:155], v[40:43]
	v_mfma_f32_16x16x32_bf16 v[32:35], v[214:217], v[152:155], v[32:35]
	v_mfma_f32_16x16x32_bf16 v[24:27], v[206:209], v[170:173], v[24:27]
	v_mfma_f32_16x16x32_bf16 v[16:19], v[214:217], v[170:173], v[16:19]
	v_mfma_f32_16x16x32_bf16 v[8:11], v[206:209], v[192:195], v[8:11]
	v_mfma_f32_16x16x32_bf16 v[0:3], v[214:217], v[192:195], v[0:3]
	v_mfma_f32_16x16x32_bf16 v[56:59], v[210:213], v[148:151], v[56:59]
	v_mfma_f32_16x16x32_bf16 v[48:51], v[232:235], v[148:151], v[48:51]
	v_mfma_f32_16x16x32_bf16 v[40:43], v[210:213], v[166:169], v[40:43]
	v_mfma_f32_16x16x32_bf16 v[32:35], v[232:235], v[166:169], v[32:35]
	v_mfma_f32_16x16x32_bf16 v[24:27], v[210:213], v[188:191], v[24:27]
	v_mfma_f32_16x16x32_bf16 v[16:19], v[232:235], v[188:191], v[16:19]
	v_mfma_f32_16x16x32_bf16 v[8:11], v[210:213], v[202:205], v[8:11]
	v_mfma_f32_16x16x32_bf16 v[0:3], v[232:235], v[202:205], v[0:3]
	s_add_i32 s28, 0, 0x18000
	v_add_u32_e32 v140, s28, v200
	s_barrier
	ds_read_b128 v[128:131], v140
	ds_read_b128 v[132:135], v140 offset:1024
	ds_read_b128 v[136:139], v140 offset:2048
	ds_read_b128 v[140:143], v140 offset:3072
	s_add_u32 s52, s52, 0x40000
	s_addc_u32 s53, s53, 0
	s_mov_b32 m0, s58
	v_lshl_add_u64 v[206:207], s[52:53], 0, v[156:157]
	ds_read_b128 v[144:147], v201 offset:32768
	ds_read_b128 v[152:155], v201 offset:34816
	ds_read_b128 v[170:173], v201 offset:36864
	ds_read_b128 v[192:195], v201 offset:38912
	ds_read_b128 v[148:151], v201 offset:33792
	ds_read_b128 v[166:169], v201 offset:35840
	ds_read_b128 v[188:191], v201 offset:37888
	ds_read_b128 v[202:205], v201 offset:39936
	global_load_lds_dwordx4 v[206:207], off
	v_lshl_add_u64 v[206:207], s[52:53], 0, v[158:159]
	s_mov_b32 m0, s59
	s_nop 0
	global_load_lds_dwordx4 v[206:207], off
	s_waitcnt lgkmcnt(8)
	s_barrier
	s_waitcnt lgkmcnt(6)
	v_mfma_f32_16x16x32_bf16 v[124:127], v[128:131], v[144:147], v[124:127]
	v_mfma_f32_16x16x32_bf16 v[116:119], v[136:139], v[144:147], v[116:119]
	v_mfma_f32_16x16x32_bf16 v[108:111], v[128:131], v[152:155], v[108:111]
	v_mfma_f32_16x16x32_bf16 v[100:103], v[136:139], v[152:155], v[100:103]
	s_waitcnt lgkmcnt(4)
	v_mfma_f32_16x16x32_bf16 v[92:95], v[128:131], v[170:173], v[92:95]
	v_mfma_f32_16x16x32_bf16 v[84:87], v[136:139], v[170:173], v[84:87]
	v_mfma_f32_16x16x32_bf16 v[76:79], v[128:131], v[192:195], v[76:79]
	v_mfma_f32_16x16x32_bf16 v[68:71], v[136:139], v[192:195], v[68:71]
	s_waitcnt lgkmcnt(2)
	v_mfma_f32_16x16x32_bf16 v[124:127], v[132:135], v[148:151], v[124:127]
	v_mfma_f32_16x16x32_bf16 v[116:119], v[140:143], v[148:151], v[116:119]
	v_mfma_f32_16x16x32_bf16 v[108:111], v[132:135], v[166:169], v[108:111]
	v_mfma_f32_16x16x32_bf16 v[100:103], v[140:143], v[166:169], v[100:103]
	s_waitcnt lgkmcnt(0)
	v_mfma_f32_16x16x32_bf16 v[92:95], v[132:135], v[188:191], v[92:95]
	v_mfma_f32_16x16x32_bf16 v[84:87], v[140:143], v[188:191], v[84:87]
	v_mfma_f32_16x16x32_bf16 v[76:79], v[132:135], v[202:205], v[76:79]
	v_mfma_f32_16x16x32_bf16 v[68:71], v[140:143], v[202:205], v[68:71]
	s_barrier
	s_add_i32 s29, 0, 0x1c000
	s_add_i32 s28, s28, s55
	v_add_u32_e32 v232, s29, v200
	v_lshl_add_u64 v[174:175], v[174:175], 0, s[40:41]
	s_mov_b32 m0, s28
	ds_read_b128 v[206:209], v232
	ds_read_b128 v[210:213], v232 offset:1024
	ds_read_b128 v[214:217], v232 offset:2048
	ds_read_b128 v[232:235], v232 offset:3072
	global_load_lds_dwordx4 v[174:175], off
	v_lshl_add_u64 v[174:175], v[196:197], 0, s[40:41]
	s_add_i32 m0, s28, 0x2000
	s_nop 0
	global_load_lds_dwordx4 v[174:175], off
	s_barrier
	s_waitcnt lgkmcnt(1)
	v_mfma_f32_16x16x32_bf16 v[120:123], v[206:209], v[144:147], v[120:123]
	v_mfma_f32_16x16x32_bf16 v[112:115], v[214:217], v[144:147], v[112:115]
	v_mfma_f32_16x16x32_bf16 v[104:107], v[206:209], v[152:155], v[104:107]
	v_mfma_f32_16x16x32_bf16 v[96:99], v[214:217], v[152:155], v[96:99]
	v_mfma_f32_16x16x32_bf16 v[88:91], v[206:209], v[170:173], v[88:91]
	v_mfma_f32_16x16x32_bf16 v[80:83], v[214:217], v[170:173], v[80:83]
	v_mfma_f32_16x16x32_bf16 v[72:75], v[206:209], v[192:195], v[72:75]
	v_mfma_f32_16x16x32_bf16 v[64:67], v[214:217], v[192:195], v[64:67]
	s_waitcnt lgkmcnt(0)
	v_mfma_f32_16x16x32_bf16 v[120:123], v[210:213], v[148:151], v[120:123]
	v_mfma_f32_16x16x32_bf16 v[112:115], v[232:235], v[148:151], v[112:115]
	v_mfma_f32_16x16x32_bf16 v[104:107], v[210:213], v[166:169], v[104:107]
	v_mfma_f32_16x16x32_bf16 v[96:99], v[232:235], v[166:169], v[96:99]
	v_mfma_f32_16x16x32_bf16 v[88:91], v[210:213], v[188:191], v[88:91]
	v_mfma_f32_16x16x32_bf16 v[80:83], v[232:235], v[188:191], v[80:83]
	v_mfma_f32_16x16x32_bf16 v[72:75], v[210:213], v[202:205], v[72:75]
	v_mfma_f32_16x16x32_bf16 v[64:67], v[232:235], v[202:205], v[64:67]
	s_mov_b32 m0, s62
	v_lshl_add_u64 v[174:175], v[236:237], 0, s[40:41]
	s_barrier
	ds_read_b128 v[144:147], v201 offset:49152
	ds_read_b128 v[152:155], v201 offset:51200
	ds_read_b128 v[170:173], v201 offset:53248
	ds_read_b128 v[192:195], v201 offset:55296
	ds_read_b128 v[148:151], v201 offset:50176
	ds_read_b128 v[166:169], v201 offset:52224
	ds_read_b128 v[188:191], v201 offset:54272
	ds_read_b128 v[202:205], v201 offset:56320
	global_load_lds_dwordx4 v[174:175], off
	v_lshl_add_u64 v[174:175], v[238:239], 0, s[40:41]
	s_mov_b32 m0, s63
	s_nop 0
	global_load_lds_dwordx4 v[174:175], off
	s_barrier
	s_waitcnt lgkmcnt(6)
	v_mfma_f32_16x16x32_bf16 v[60:63], v[128:131], v[144:147], v[60:63]
	v_mfma_f32_16x16x32_bf16 v[52:55], v[136:139], v[144:147], v[52:55]
	v_mfma_f32_16x16x32_bf16 v[44:47], v[128:131], v[152:155], v[44:47]
	v_mfma_f32_16x16x32_bf16 v[36:39], v[136:139], v[152:155], v[36:39]
	s_waitcnt lgkmcnt(4)
	v_mfma_f32_16x16x32_bf16 v[28:31], v[128:131], v[170:173], v[28:31]
	v_mfma_f32_16x16x32_bf16 v[20:23], v[136:139], v[170:173], v[20:23]
	v_mfma_f32_16x16x32_bf16 v[12:15], v[128:131], v[192:195], v[12:15]
	v_mfma_f32_16x16x32_bf16 v[4:7], v[136:139], v[192:195], v[4:7]
	s_waitcnt lgkmcnt(2)
	v_mfma_f32_16x16x32_bf16 v[60:63], v[132:135], v[148:151], v[60:63]
	v_mfma_f32_16x16x32_bf16 v[52:55], v[140:143], v[148:151], v[52:55]
	v_mfma_f32_16x16x32_bf16 v[44:47], v[132:135], v[166:169], v[44:47]
	v_mfma_f32_16x16x32_bf16 v[36:39], v[140:143], v[166:169], v[36:39]
	s_waitcnt lgkmcnt(0)
	v_mfma_f32_16x16x32_bf16 v[28:31], v[132:135], v[188:191], v[28:31]
	v_mfma_f32_16x16x32_bf16 v[20:23], v[140:143], v[188:191], v[20:23]
	v_mfma_f32_16x16x32_bf16 v[12:15], v[132:135], v[202:205], v[12:15]
	v_mfma_f32_16x16x32_bf16 v[4:7], v[140:143], v[202:205], v[4:7]
	s_barrier
	s_add_u32 s50, s50, 0x40080
	s_addc_u32 s51, s51, 0
	s_add_i32 s28, s29, s55
	v_lshl_add_u64 v[128:129], s[50:51], 0, v[176:177]
	s_mov_b32 m0, s28
	s_nop 0
	global_load_lds_dwordx4 v[128:129], off
	v_lshl_add_u64 v[128:129], s[50:51], 0, v[160:161]
	s_add_i32 m0, s28, 0x2000
	s_nop 0
	global_load_lds_dwordx4 v[128:129], off
	s_waitcnt vmcnt(6)
	s_barrier
	v_mfma_f32_16x16x32_bf16 v[56:59], v[206:209], v[144:147], v[56:59]
	v_mfma_f32_16x16x32_bf16 v[48:51], v[214:217], v[144:147], v[48:51]
	v_mfma_f32_16x16x32_bf16 v[40:43], v[206:209], v[152:155], v[40:43]
	v_mfma_f32_16x16x32_bf16 v[32:35], v[214:217], v[152:155], v[32:35]
	v_mfma_f32_16x16x32_bf16 v[24:27], v[206:209], v[170:173], v[24:27]
	v_mfma_f32_16x16x32_bf16 v[16:19], v[214:217], v[170:173], v[16:19]
	v_mfma_f32_16x16x32_bf16 v[8:11], v[206:209], v[192:195], v[8:11]
	v_mfma_f32_16x16x32_bf16 v[0:3], v[214:217], v[192:195], v[0:3]
	v_mfma_f32_16x16x32_bf16 v[56:59], v[210:213], v[148:151], v[56:59]
	v_mfma_f32_16x16x32_bf16 v[48:51], v[232:235], v[148:151], v[48:51]
	v_mfma_f32_16x16x32_bf16 v[40:43], v[210:213], v[166:169], v[40:43]
	v_mfma_f32_16x16x32_bf16 v[32:35], v[232:235], v[166:169], v[32:35]
	v_mfma_f32_16x16x32_bf16 v[24:27], v[210:213], v[188:191], v[24:27]
	v_mfma_f32_16x16x32_bf16 v[16:19], v[232:235], v[188:191], v[16:19]
	v_mfma_f32_16x16x32_bf16 v[8:11], v[210:213], v[202:205], v[8:11]
	v_mfma_f32_16x16x32_bf16 v[0:3], v[232:235], v[202:205], v[0:3]
	s_add_i32 s70, s70, 2
	s_add_u32 s6, s6, 0x100
	s_addc_u32 s7, s7, 0
	s_add_u32 s68, s68, 0x100
	s_addc_u32 s69, s69, 0
	s_cmp_lt_u32 s70, 14
	s_barrier
	s_cbranch_scc1 .LBB0_1436
	v_mov_b32_e32 v134, v199
	v_mov_b32_e32 v128, v198
	s_lshl_b32 s4, s4, 8
	s_add_i32 s4, s4, s60
	v_add_u32_e32 v192, s4, v128
	v_lshlrev_b32_e32 v128, 2, v134
	v_ashrrev_i32_e32 v129, 31, v128
	v_ashrrev_i32_e32 v193, 31, v192
	v_add_u32_e32 v190, 16, v192
	v_lshl_add_u64 v[132:133], v[128:129], 2, s[8:9]
	v_lshlrev_b64 v[128:129], 6, v[192:193]
	v_ashrrev_i32_e32 v191, 31, v190
	v_add_u32_e32 v188, 32, v192
	v_lshl_add_u64 v[128:129], v[132:133], 0, v[128:129]
	v_lshlrev_b64 v[130:131], 6, v[190:191]
	v_ashrrev_i32_e32 v189, 31, v188
	v_lshl_add_u64 v[130:131], v[132:133], 0, v[130:131]
	global_load_dwordx4 v[202:205], v[128:129], off
	global_load_dwordx4 v[144:147], v[130:131], off
	v_lshlrev_b64 v[128:129], 6, v[188:189]
	v_add_u32_e32 v174, 48, v192
	v_lshl_add_u64 v[128:129], v[132:133], 0, v[128:129]
	v_ashrrev_i32_e32 v175, 31, v174
	global_load_dwordx4 v[148:151], v[128:129], off
	v_lshlrev_b64 v[128:129], 6, v[174:175]
	v_lshl_add_u64 v[128:129], v[132:133], 0, v[128:129]
	global_load_dwordx4 v[152:155], v[128:129], off
	v_add_u32_e32 v172, 0x80, v192
	v_ashrrev_i32_e32 v173, 31, v172
	v_lshlrev_b64 v[128:129], 6, v[172:173]
	v_lshl_add_u64 v[128:129], v[132:133], 0, v[128:129]
	global_load_dwordx4 v[140:143], v[128:129], off
	v_add_u32_e32 v170, 0x90, v192
	v_ashrrev_i32_e32 v171, 31, v170
	v_lshlrev_b64 v[128:129], 6, v[170:171]
	v_lshl_add_u64 v[128:129], v[132:133], 0, v[128:129]
	global_load_dwordx4 v[128:131], v[128:129], off
	s_lshl_b32 s5, s5, 7
	v_add_u32_e32 v168, 0xa0, v192
	v_add_u32_e32 v166, 0xb0, v192
	s_or_b32 s5, s5, s61
	v_ashrrev_i32_e32 v169, 31, v168
	v_ashrrev_i32_e32 v167, 31, v166
	v_lshl_add_u32 v194, v134, 3, s5
	v_lshlrev_b64 v[134:135], 6, v[168:169]
	v_lshlrev_b64 v[136:137], 6, v[166:167]
	v_lshl_add_u64 v[134:135], v[132:133], 0, v[134:135]
	v_lshl_add_u64 v[132:133], v[132:133], 0, v[136:137]
	global_load_dwordx4 v[136:139], v[134:135], off
	s_nop 0
	global_load_dwordx4 v[132:135], v[132:133], off
	s_mov_b32 s4, 0x358637bd
	v_mov_b64_e32 v[196:197], s[4:5]
	v_ashrrev_i32_e32 v195, 31, v194
	s_mov_b64 s[50:51], s[20:21]
	s_waitcnt vmcnt(0)
	v_mov_b32_e32 v206, v203
	v_mov_b32_e32 v207, v204
	v_mov_b32_e32 v203, v205
	v_mov_b32_e32 v204, v145
	v_mov_b32_e32 v205, v146
	v_mov_b32_e32 v145, v147
	v_pk_add_f32 v[202:203], v[206:207], v[202:203]
	v_mov_b32_e32 v146, v149
	v_mov_b32_e32 v147, v150
	v_mov_b32_e32 v149, v151
	v_mov_b32_e32 v150, v153
	v_mov_b32_e32 v151, v154
	v_mov_b32_e32 v153, v155
	v_pk_add_f32 v[144:145], v[204:205], v[144:145]
	v_mov_b32_e32 v155, v202
	v_pk_add_f32 v[146:147], v[146:147], v[148:149]
	v_pk_add_f32 v[148:149], v[150:151], v[152:153]
	v_mov_b32_e32 v154, v144
	v_mov_b32_e32 v202, v145
	v_mov_b32_e32 v144, v148
	v_mov_b32_e32 v145, v146
	v_mov_b32_e32 v146, v149
	v_pk_add_f32 v[148:149], v[154:155], v[202:203]
	v_pk_add_f32 v[144:145], v[144:145], v[146:147]
	ds_bpermute_b32 v147, v219, v149
	ds_bpermute_b32 v146, v219, v148
	ds_bpermute_b32 v151, v219, v145
	ds_bpermute_b32 v150, v219, v144
	v_mov_b32_e32 v152, v141
	v_mov_b32_e32 v153, v142
	v_mov_b32_e32 v141, v143
	s_waitcnt lgkmcnt(0)
	v_pk_add_f32 v[142:143], v[148:149], v[146:147]
	ds_bpermute_b32 v147, v218, v143
	ds_bpermute_b32 v146, v218, v142
	v_pk_add_f32 v[144:145], v[144:145], v[150:151]
	ds_bpermute_b32 v149, v218, v145
	ds_bpermute_b32 v148, v218, v144
	v_mov_b32_e32 v150, v129
	s_waitcnt lgkmcnt(2)
	v_pk_add_f32 v[142:143], v[142:143], v[146:147]
	v_mov_b32_e32 v151, v130
	v_pk_fma_f32 v[142:143], v[142:143], s[30:31], v[196:197] op_sel_hi:[1,0,0]
	s_waitcnt lgkmcnt(0)
	v_pk_add_f32 v[144:145], v[144:145], v[148:149]
	v_mul_f32_e32 v129, 0x4b800000, v143
	v_cmp_gt_f32_e32 vcc, s86, v143
	v_pk_fma_f32 v[146:147], v[144:145], s[30:31], v[196:197] op_sel_hi:[1,0,0]
	v_mul_f32_e32 v130, 0x4b800000, v142
	v_cndmask_b32_e32 v129, v143, v129, vcc
	v_rsq_f32_e32 v129, v129
	v_cmp_gt_f32_e64 s[4:5], s86, v142
	v_mul_f32_e32 v144, 0x4b800000, v147
	v_cmp_gt_f32_e64 s[6:7], s86, v147
	v_cndmask_b32_e64 v130, v142, v130, s[4:5]
	v_rsq_f32_e32 v142, v130
	v_cndmask_b32_e64 v130, v147, v144, s[6:7]
	v_rsq_f32_e32 v143, v130
	v_mul_f32_e32 v130, 0x45800000, v129
	v_cndmask_b32_e32 v144, v129, v130, vcc
	v_mov_b32_e32 v129, v131
	v_pk_add_f32 v[140:141], v[152:153], v[140:141]
	v_pk_add_f32 v[128:129], v[150:151], v[128:129]
	v_mov_b32_e32 v131, v140
	v_mov_b32_e32 v130, v128
	v_mov_b32_e32 v140, v129
	v_pk_add_f32 v[128:129], v[130:131], v[140:141]
	ds_bpermute_b32 v131, v219, v129
	ds_bpermute_b32 v130, v219, v128
	v_mul_f32_e32 v145, 0x45800000, v142
	v_cndmask_b32_e64 v142, v142, v145, s[4:5]
	v_mul_f32_e32 v140, 0x4b800000, v146
	v_cmp_gt_f32_e32 vcc, s86, v146
	s_waitcnt lgkmcnt(0)
	v_pk_add_f32 v[128:129], v[128:129], v[130:131]
	ds_bpermute_b32 v131, v218, v129
	ds_bpermute_b32 v130, v218, v128
	v_cndmask_b32_e32 v140, v146, v140, vcc
	v_rsq_f32_e32 v141, v140
	v_mul_f32_e32 v140, 0x45800000, v143
	v_cndmask_b32_e64 v140, v143, v140, s[6:7]
	s_waitcnt lgkmcnt(0)
	v_pk_add_f32 v[128:129], v[128:129], v[130:131]
	v_mov_b32_e32 v131, v138
	v_pk_fma_f32 v[128:129], v[128:129], s[30:31], v[196:197] op_sel_hi:[1,0,0]
	v_mul_f32_e32 v143, 0x45800000, v141
	v_mul_f32_e32 v130, 0x4b800000, v129
	v_cmp_gt_f32_e64 s[4:5], s86, v129
	v_cmp_gt_f32_e64 s[6:7], s86, v128
	v_pk_mul_f32 v[110:111], v[110:111], v[142:143] op_sel_hi:[1,0]
	v_cndmask_b32_e64 v129, v129, v130, s[4:5]
	v_mov_b32_e32 v130, v137
	v_mov_b32_e32 v137, v139
	v_pk_add_f32 v[130:131], v[130:131], v[136:137]
	v_mov_b32_e32 v136, v133
	v_mov_b32_e32 v137, v134
	v_mov_b32_e32 v133, v135
	v_pk_add_f32 v[132:133], v[136:137], v[132:133]
	v_mov_b32_e32 v135, v130
	v_mov_b32_e32 v134, v132
	v_mov_b32_e32 v130, v133
	v_pk_add_f32 v[130:131], v[134:135], v[130:131]
	ds_bpermute_b32 v133, v219, v131
	ds_bpermute_b32 v132, v219, v130
	v_rsq_f32_e32 v145, v129
	v_mul_f32_e32 v129, 0x4b800000, v128
	v_cndmask_b32_e64 v128, v128, v129, s[6:7]
	v_rsq_f32_e32 v135, v128
	s_waitcnt lgkmcnt(0)
	v_pk_add_f32 v[128:129], v[130:131], v[132:133]
	ds_bpermute_b32 v131, v218, v129
	ds_bpermute_b32 v130, v218, v128
	v_pk_mul_f32 v[126:127], v[126:127], v[144:145] op_sel_hi:[1,0]
	v_pk_mul_f32 v[122:123], v[122:123], v[144:145] op_sel_hi:[1,0]
	v_pk_mul_f32 v[116:117], v[116:117], v[144:145] op_sel_hi:[1,0]
	v_pk_mul_f32 v[124:125], v[124:125], v[144:145] op_sel_hi:[1,0]
	v_pk_mul_f32 v[138:139], v[126:127], s[44:45] op_sel_hi:[1,0]
	v_pk_mul_f32 v[120:121], v[120:121], v[144:145] op_sel_hi:[1,0]
	v_pk_mul_f32 v[122:123], v[126:127], v[122:123]
	v_pk_mul_f32 v[118:119], v[118:119], v[144:145] op_sel_hi:[1,0]
	v_pk_mul_f32 v[126:127], v[116:117], s[44:45] op_sel_hi:[1,0]
	v_pk_mul_f32 v[146:147], v[124:125], s[44:45] op_sel_hi:[1,0]
	v_pk_mul_f32 v[120:121], v[124:125], v[120:121]
	v_pk_mul_f32 v[124:125], v[118:119], s[44:45] op_sel_hi:[1,0]
	v_exp_f32_e32 v126, v126
	v_exp_f32_e32 v127, v127
	s_waitcnt lgkmcnt(0)
	v_pk_add_f32 v[128:129], v[128:129], v[130:131]
	v_exp_f32_e32 v146, v146
	v_exp_f32_e32 v138, v138
	v_exp_f32_e32 v139, v139
	v_exp_f32_e32 v147, v147
	v_exp_f32_e32 v124, v124
	v_exp_f32_e32 v125, v125
	v_pk_fma_f32 v[128:129], v[128:129], s[30:31], v[196:197] op_sel_hi:[1,0,0]
	v_cndmask_b32_e32 v136, v141, v143, vcc
	v_mul_f32_e32 v132, 0x45800000, v145
	v_mul_f32_e32 v130, 0x4b800000, v129
	v_cmp_gt_f32_e32 vcc, s86, v129
	v_cndmask_b32_e64 v134, v145, v132, s[4:5]
	v_cmp_gt_f32_e64 s[4:5], s86, v128
	v_cndmask_b32_e32 v129, v129, v130, vcc
	v_mul_f32_e32 v130, 0x4b800000, v128
	v_pk_add_f32 v[126:127], v[126:127], 1.0 op_sel_hi:[1,0]
	v_rsq_f32_e32 v129, v129
	v_cndmask_b32_e64 v128, v128, v130, s[4:5]
	v_pk_add_f32 v[138:139], v[138:139], 1.0 op_sel_hi:[1,0]
	v_pk_add_f32 v[146:147], v[146:147], 1.0 op_sel_hi:[1,0]
	v_pk_add_f32 v[124:125], v[124:125], 1.0 op_sel_hi:[1,0]
	v_rcp_f32_e32 v126, v126
	v_rcp_f32_e32 v127, v127
	v_rsq_f32_e32 v128, v128
	v_rcp_f32_e32 v146, v146
	v_rcp_f32_e32 v138, v138
	v_rcp_f32_e32 v139, v139
	v_rcp_f32_e32 v147, v147
	v_rcp_f32_e32 v124, v124
	v_rcp_f32_e32 v125, v125
	v_pk_mul_f32 v[112:113], v[112:113], v[144:145] op_sel_hi:[1,0]
	v_pk_mul_f32 v[114:115], v[114:115], v[144:145] op_sel_hi:[1,0]
	v_pk_mul_f32 v[112:113], v[116:117], v[112:113]
	v_mul_f32_e32 v130, 0x45800000, v129
	v_pk_mul_f32 v[114:115], v[118:119], v[114:115]
	v_pk_mul_f32 v[112:113], v[112:113], v[126:127]
	v_cndmask_b32_e32 v130, v129, v130, vcc
	v_mul_f32_e32 v129, 0x45800000, v128
	v_pk_mul_f32 v[122:123], v[122:123], v[138:139]
	v_pk_mul_f32 v[120:121], v[120:121], v[146:147]
	v_pk_mul_f32 v[114:115], v[114:115], v[124:125]
	v_cvt_pk_bf16_f32 v116, v120, v121
	v_cvt_pk_bf16_f32 v117, v122, v123
	v_cvt_pk_bf16_f32 v118, v112, v113
	v_mov_b64_e32 v[112:113], s[10:11]
	v_cndmask_b32_e64 v128, v128, v129, s[4:5]
	v_cvt_pk_bf16_f32 v119, v114, v115
	v_mad_i64_i32 v[120:121], s[4:5], v192, s35, v[112:113]
	v_lshlrev_b64 v[114:115], 1, v[194:195]
	v_lshl_add_u64 v[120:121], v[120:121], 0, v[114:115]
	v_pk_mul_f32 v[108:109], v[108:109], v[142:143] op_sel_hi:[1,0]
	v_pk_mul_f32 v[106:107], v[106:107], v[142:143] op_sel_hi:[1,0]
	v_pk_mul_f32 v[104:105], v[104:105], v[142:143] op_sel_hi:[1,0]
	v_pk_mul_f32 v[102:103], v[102:103], v[142:143] op_sel_hi:[1,0]
	v_pk_mul_f32 v[100:101], v[100:101], v[142:143] op_sel_hi:[1,0]
	global_store_dwordx4 v[120:121], v[116:119], off
	v_pk_mul_f32 v[104:105], v[108:109], v[104:105]
	v_pk_mul_f32 v[106:107], v[110:111], v[106:107]
	v_pk_mul_f32 v[116:117], v[110:111], s[44:45] op_sel_hi:[1,0]
	v_pk_mul_f32 v[118:119], v[108:109], s[44:45] op_sel_hi:[1,0]
	v_pk_mul_f32 v[108:109], v[102:103], s[44:45] op_sel_hi:[1,0]
	v_pk_mul_f32 v[110:111], v[100:101], s[44:45] op_sel_hi:[1,0]
	v_exp_f32_e32 v108, v108
	v_exp_f32_e32 v110, v110
	v_exp_f32_e32 v109, v109
	v_exp_f32_e32 v111, v111
	v_exp_f32_e32 v118, v118
	v_exp_f32_e32 v116, v116
	v_exp_f32_e32 v117, v117
	v_exp_f32_e32 v119, v119
	v_pk_add_f32 v[108:109], v[108:109], 1.0 op_sel_hi:[1,0]
	v_pk_add_f32 v[110:111], v[110:111], 1.0 op_sel_hi:[1,0]
	v_pk_add_f32 v[116:117], v[116:117], 1.0 op_sel_hi:[1,0]
	v_pk_add_f32 v[118:119], v[118:119], 1.0 op_sel_hi:[1,0]
	v_rcp_f32_e32 v110, v110
	v_rcp_f32_e32 v108, v108
	v_rcp_f32_e32 v109, v109
	v_rcp_f32_e32 v111, v111
	v_rcp_f32_e32 v118, v118
	v_rcp_f32_e32 v116, v116
	v_rcp_f32_e32 v117, v117
	v_rcp_f32_e32 v119, v119
	v_pk_mul_f32 v[98:99], v[98:99], v[142:143] op_sel_hi:[1,0]
	v_pk_mul_f32 v[96:97], v[96:97], v[142:143] op_sel_hi:[1,0]
	v_pk_mul_f32 v[98:99], v[102:103], v[98:99]
	v_pk_mul_f32 v[96:97], v[100:101], v[96:97]
	v_pk_mul_f32 v[100:101], v[98:99], v[108:109]
	v_pk_mul_f32 v[98:99], v[96:97], v[110:111]
	v_pk_mul_f32 v[106:107], v[106:107], v[116:117]
	v_pk_mul_f32 v[104:105], v[104:105], v[118:119]
	v_pk_mul_f32 v[94:95], v[94:95], v[140:141] op_sel_hi:[1,0]
	v_cvt_pk_bf16_f32 v96, v104, v105
	v_cvt_pk_bf16_f32 v97, v106, v107
	v_cvt_pk_bf16_f32 v98, v98, v99
	v_cvt_pk_bf16_f32 v99, v100, v101
	v_mad_i64_i32 v[100:101], s[4:5], v190, s35, v[112:113]
	v_lshl_add_u64 v[100:101], v[100:101], 0, v[114:115]
	v_pk_mul_f32 v[92:93], v[92:93], v[140:141] op_sel_hi:[1,0]
	v_pk_mul_f32 v[90:91], v[90:91], v[140:141] op_sel_hi:[1,0]
	v_pk_mul_f32 v[88:89], v[88:89], v[140:141] op_sel_hi:[1,0]
	v_pk_mul_f32 v[86:87], v[86:87], v[140:141] op_sel_hi:[1,0]
	v_pk_mul_f32 v[84:85], v[84:85], v[140:141] op_sel_hi:[1,0]
	global_store_dwordx4 v[100:101], v[96:99], off
	v_pk_mul_f32 v[88:89], v[92:93], v[88:89]
	v_pk_mul_f32 v[90:91], v[94:95], v[90:91]
	v_pk_mul_f32 v[96:97], v[94:95], s[44:45] op_sel_hi:[1,0]
	v_pk_mul_f32 v[98:99], v[92:93], s[44:45] op_sel_hi:[1,0]
	v_pk_mul_f32 v[92:93], v[86:87], s[44:45] op_sel_hi:[1,0]
	v_pk_mul_f32 v[94:95], v[84:85], s[44:45] op_sel_hi:[1,0]
	v_exp_f32_e32 v92, v92
	v_exp_f32_e32 v94, v94
	v_exp_f32_e32 v93, v93
	v_exp_f32_e32 v95, v95
	v_exp_f32_e32 v98, v98
	v_exp_f32_e32 v96, v96
	v_exp_f32_e32 v97, v97
	v_exp_f32_e32 v99, v99
	v_pk_add_f32 v[92:93], v[92:93], 1.0 op_sel_hi:[1,0]
	v_pk_add_f32 v[94:95], v[94:95], 1.0 op_sel_hi:[1,0]
	v_pk_add_f32 v[96:97], v[96:97], 1.0 op_sel_hi:[1,0]
	v_pk_add_f32 v[98:99], v[98:99], 1.0 op_sel_hi:[1,0]
	v_rcp_f32_e32 v94, v94
	v_rcp_f32_e32 v92, v92
	v_rcp_f32_e32 v93, v93
	v_rcp_f32_e32 v95, v95
	v_rcp_f32_e32 v98, v98
	v_rcp_f32_e32 v96, v96
	v_rcp_f32_e32 v97, v97
	v_rcp_f32_e32 v99, v99
	v_pk_mul_f32 v[82:83], v[82:83], v[140:141] op_sel_hi:[1,0]
	v_pk_mul_f32 v[80:81], v[80:81], v[140:141] op_sel_hi:[1,0]
	v_pk_mul_f32 v[82:83], v[86:87], v[82:83]
	v_pk_mul_f32 v[80:81], v[84:85], v[80:81]
	v_pk_mul_f32 v[84:85], v[82:83], v[92:93]
	v_pk_mul_f32 v[82:83], v[80:81], v[94:95]
	v_pk_mul_f32 v[90:91], v[90:91], v[96:97]
	v_pk_mul_f32 v[88:89], v[88:89], v[98:99]
	v_pk_mul_f32 v[78:79], v[78:79], v[136:137] op_sel_hi:[1,0]
	v_cvt_pk_bf16_f32 v80, v88, v89
	v_cvt_pk_bf16_f32 v81, v90, v91
	v_cvt_pk_bf16_f32 v82, v82, v83
	v_cvt_pk_bf16_f32 v83, v84, v85
	v_mad_i64_i32 v[84:85], s[4:5], v188, s35, v[112:113]
	v_lshl_add_u64 v[84:85], v[84:85], 0, v[114:115]
	v_pk_mul_f32 v[76:77], v[76:77], v[136:137] op_sel_hi:[1,0]
	v_pk_mul_f32 v[74:75], v[74:75], v[136:137] op_sel_hi:[1,0]
	v_pk_mul_f32 v[72:73], v[72:73], v[136:137] op_sel_hi:[1,0]
	v_pk_mul_f32 v[70:71], v[70:71], v[136:137] op_sel_hi:[1,0]
	v_pk_mul_f32 v[68:69], v[68:69], v[136:137] op_sel_hi:[1,0]
	global_store_dwordx4 v[84:85], v[80:83], off
	v_pk_mul_f32 v[72:73], v[76:77], v[72:73]
	v_pk_mul_f32 v[74:75], v[78:79], v[74:75]
	v_pk_mul_f32 v[80:81], v[78:79], s[44:45] op_sel_hi:[1,0]
	v_pk_mul_f32 v[82:83], v[76:77], s[44:45] op_sel_hi:[1,0]
	v_pk_mul_f32 v[76:77], v[70:71], s[44:45] op_sel_hi:[1,0]
	v_pk_mul_f32 v[78:79], v[68:69], s[44:45] op_sel_hi:[1,0]
	v_exp_f32_e32 v76, v76
	v_exp_f32_e32 v78, v78
	v_exp_f32_e32 v77, v77
	v_exp_f32_e32 v79, v79
	v_exp_f32_e32 v82, v82
	v_exp_f32_e32 v80, v80
	v_exp_f32_e32 v81, v81
	v_exp_f32_e32 v83, v83
	v_pk_add_f32 v[76:77], v[76:77], 1.0 op_sel_hi:[1,0]
	v_pk_add_f32 v[78:79], v[78:79], 1.0 op_sel_hi:[1,0]
	v_pk_add_f32 v[80:81], v[80:81], 1.0 op_sel_hi:[1,0]
	v_pk_add_f32 v[82:83], v[82:83], 1.0 op_sel_hi:[1,0]
	v_rcp_f32_e32 v78, v78
	v_rcp_f32_e32 v76, v76
	v_rcp_f32_e32 v77, v77
	v_rcp_f32_e32 v79, v79
	v_rcp_f32_e32 v82, v82
	v_rcp_f32_e32 v80, v80
	v_rcp_f32_e32 v81, v81
	v_rcp_f32_e32 v83, v83
	v_pk_mul_f32 v[66:67], v[66:67], v[136:137] op_sel_hi:[1,0]
	v_pk_mul_f32 v[64:65], v[64:65], v[136:137] op_sel_hi:[1,0]
	v_pk_mul_f32 v[66:67], v[70:71], v[66:67]
	v_pk_mul_f32 v[64:65], v[68:69], v[64:65]
	v_pk_mul_f32 v[68:69], v[66:67], v[76:77]
	v_pk_mul_f32 v[66:67], v[64:65], v[78:79]
	v_pk_mul_f32 v[74:75], v[74:75], v[80:81]
	v_pk_mul_f32 v[72:73], v[72:73], v[82:83]
	v_pk_mul_f32 v[62:63], v[62:63], v[134:135] op_sel_hi:[1,0]
	v_cvt_pk_bf16_f32 v64, v72, v73
	v_cvt_pk_bf16_f32 v65, v74, v75
	v_cvt_pk_bf16_f32 v66, v66, v67
	v_cvt_pk_bf16_f32 v67, v68, v69
	v_mad_i64_i32 v[68:69], s[4:5], v174, s35, v[112:113]
	v_lshl_add_u64 v[68:69], v[68:69], 0, v[114:115]
	v_pk_mul_f32 v[60:61], v[60:61], v[134:135] op_sel_hi:[1,0]
	v_pk_mul_f32 v[58:59], v[58:59], v[134:135] op_sel_hi:[1,0]
	v_pk_mul_f32 v[56:57], v[56:57], v[134:135] op_sel_hi:[1,0]
	v_pk_mul_f32 v[54:55], v[54:55], v[134:135] op_sel_hi:[1,0]
	v_pk_mul_f32 v[52:53], v[52:53], v[134:135] op_sel_hi:[1,0]
	global_store_dwordx4 v[68:69], v[64:67], off
	v_pk_mul_f32 v[56:57], v[60:61], v[56:57]
	v_pk_mul_f32 v[58:59], v[62:63], v[58:59]
	v_pk_mul_f32 v[64:65], v[62:63], s[44:45] op_sel_hi:[1,0]
	v_pk_mul_f32 v[66:67], v[60:61], s[44:45] op_sel_hi:[1,0]
	v_pk_mul_f32 v[60:61], v[54:55], s[44:45] op_sel_hi:[1,0]
	v_pk_mul_f32 v[62:63], v[52:53], s[44:45] op_sel_hi:[1,0]
	v_exp_f32_e32 v60, v60
	v_exp_f32_e32 v62, v62
	v_exp_f32_e32 v61, v61
	v_exp_f32_e32 v63, v63
	v_exp_f32_e32 v66, v66
	v_exp_f32_e32 v64, v64
	v_exp_f32_e32 v65, v65
	v_exp_f32_e32 v67, v67
	v_pk_add_f32 v[60:61], v[60:61], 1.0 op_sel_hi:[1,0]
	v_pk_add_f32 v[62:63], v[62:63], 1.0 op_sel_hi:[1,0]
	v_pk_add_f32 v[64:65], v[64:65], 1.0 op_sel_hi:[1,0]
	v_pk_add_f32 v[66:67], v[66:67], 1.0 op_sel_hi:[1,0]
	v_rcp_f32_e32 v62, v62
	v_rcp_f32_e32 v60, v60
	v_rcp_f32_e32 v61, v61
	v_rcp_f32_e32 v63, v63
	v_rcp_f32_e32 v66, v66
	v_rcp_f32_e32 v64, v64
	v_rcp_f32_e32 v65, v65
	v_rcp_f32_e32 v67, v67
	v_pk_mul_f32 v[50:51], v[50:51], v[134:135] op_sel_hi:[1,0]
	v_pk_mul_f32 v[48:49], v[48:49], v[134:135] op_sel_hi:[1,0]
	v_pk_mul_f32 v[50:51], v[54:55], v[50:51]
	v_pk_mul_f32 v[48:49], v[52:53], v[48:49]
	v_mul_f32_e32 v132, 0x45800000, v135
	v_pk_mul_f32 v[52:53], v[50:51], v[60:61]
	v_pk_mul_f32 v[50:51], v[48:49], v[62:63]
	v_cndmask_b32_e64 v132, v135, v132, s[6:7]
	v_pk_mul_f32 v[58:59], v[58:59], v[64:65]
	v_pk_mul_f32 v[56:57], v[56:57], v[66:67]
	v_pk_mul_f32 v[46:47], v[46:47], v[132:133] op_sel_hi:[1,0]
	v_cvt_pk_bf16_f32 v48, v56, v57
	v_cvt_pk_bf16_f32 v49, v58, v59
	v_cvt_pk_bf16_f32 v50, v50, v51
	v_cvt_pk_bf16_f32 v51, v52, v53
	v_mad_i64_i32 v[52:53], s[4:5], v172, s35, v[112:113]
	v_lshl_add_u64 v[52:53], v[52:53], 0, v[114:115]
	v_pk_mul_f32 v[44:45], v[44:45], v[132:133] op_sel_hi:[1,0]
	v_pk_mul_f32 v[42:43], v[42:43], v[132:133] op_sel_hi:[1,0]
	v_pk_mul_f32 v[40:41], v[40:41], v[132:133] op_sel_hi:[1,0]
	v_pk_mul_f32 v[38:39], v[38:39], v[132:133] op_sel_hi:[1,0]
	v_pk_mul_f32 v[36:37], v[36:37], v[132:133] op_sel_hi:[1,0]
	global_store_dwordx4 v[52:53], v[48:51], off
	v_pk_mul_f32 v[40:41], v[44:45], v[40:41]
	v_pk_mul_f32 v[42:43], v[46:47], v[42:43]
	v_pk_mul_f32 v[48:49], v[46:47], s[44:45] op_sel_hi:[1,0]
	v_pk_mul_f32 v[50:51], v[44:45], s[44:45] op_sel_hi:[1,0]
	v_pk_mul_f32 v[44:45], v[38:39], s[44:45] op_sel_hi:[1,0]
	v_pk_mul_f32 v[46:47], v[36:37], s[44:45] op_sel_hi:[1,0]
	v_exp_f32_e32 v44, v44
	v_exp_f32_e32 v46, v46
	v_exp_f32_e32 v45, v45
	v_exp_f32_e32 v47, v47
	v_exp_f32_e32 v50, v50
	v_exp_f32_e32 v48, v48
	v_exp_f32_e32 v49, v49
	v_exp_f32_e32 v51, v51
	v_pk_add_f32 v[44:45], v[44:45], 1.0 op_sel_hi:[1,0]
	v_pk_add_f32 v[46:47], v[46:47], 1.0 op_sel_hi:[1,0]
	v_pk_add_f32 v[48:49], v[48:49], 1.0 op_sel_hi:[1,0]
	v_pk_add_f32 v[50:51], v[50:51], 1.0 op_sel_hi:[1,0]
	v_rcp_f32_e32 v46, v46
	v_rcp_f32_e32 v44, v44
	v_rcp_f32_e32 v45, v45
	v_rcp_f32_e32 v47, v47
	v_rcp_f32_e32 v50, v50
	v_rcp_f32_e32 v48, v48
	v_rcp_f32_e32 v49, v49
	v_rcp_f32_e32 v51, v51
	v_pk_mul_f32 v[34:35], v[34:35], v[132:133] op_sel_hi:[1,0]
	v_pk_mul_f32 v[32:33], v[32:33], v[132:133] op_sel_hi:[1,0]
	v_pk_mul_f32 v[34:35], v[38:39], v[34:35]
	v_pk_mul_f32 v[32:33], v[36:37], v[32:33]
	v_pk_mul_f32 v[36:37], v[34:35], v[44:45]
	v_pk_mul_f32 v[34:35], v[32:33], v[46:47]
	v_pk_mul_f32 v[42:43], v[42:43], v[48:49]
	v_pk_mul_f32 v[40:41], v[40:41], v[50:51]
	v_pk_mul_f32 v[30:31], v[30:31], v[130:131] op_sel_hi:[1,0]
	v_cvt_pk_bf16_f32 v32, v40, v41
	v_cvt_pk_bf16_f32 v33, v42, v43
	v_cvt_pk_bf16_f32 v34, v34, v35
	v_cvt_pk_bf16_f32 v35, v36, v37
	v_mad_i64_i32 v[36:37], s[4:5], v170, s35, v[112:113]
	v_lshl_add_u64 v[36:37], v[36:37], 0, v[114:115]
	v_pk_mul_f32 v[28:29], v[28:29], v[130:131] op_sel_hi:[1,0]
	v_pk_mul_f32 v[26:27], v[26:27], v[130:131] op_sel_hi:[1,0]
	v_pk_mul_f32 v[24:25], v[24:25], v[130:131] op_sel_hi:[1,0]
	v_pk_mul_f32 v[22:23], v[22:23], v[130:131] op_sel_hi:[1,0]
	v_pk_mul_f32 v[20:21], v[20:21], v[130:131] op_sel_hi:[1,0]
	global_store_dwordx4 v[36:37], v[32:35], off
	v_pk_mul_f32 v[24:25], v[28:29], v[24:25]
	v_pk_mul_f32 v[26:27], v[30:31], v[26:27]
	v_pk_mul_f32 v[32:33], v[30:31], s[44:45] op_sel_hi:[1,0]
	v_pk_mul_f32 v[34:35], v[28:29], s[44:45] op_sel_hi:[1,0]
	v_pk_mul_f32 v[28:29], v[22:23], s[44:45] op_sel_hi:[1,0]
	v_pk_mul_f32 v[30:31], v[20:21], s[44:45] op_sel_hi:[1,0]
	v_exp_f32_e32 v28, v28
	v_exp_f32_e32 v30, v30
	v_exp_f32_e32 v29, v29
	v_exp_f32_e32 v31, v31
	v_exp_f32_e32 v34, v34
	v_exp_f32_e32 v32, v32
	v_exp_f32_e32 v33, v33
	v_exp_f32_e32 v35, v35
	v_pk_add_f32 v[28:29], v[28:29], 1.0 op_sel_hi:[1,0]
	v_pk_add_f32 v[30:31], v[30:31], 1.0 op_sel_hi:[1,0]
	v_pk_add_f32 v[32:33], v[32:33], 1.0 op_sel_hi:[1,0]
	v_pk_add_f32 v[34:35], v[34:35], 1.0 op_sel_hi:[1,0]
	v_rcp_f32_e32 v30, v30
	v_rcp_f32_e32 v28, v28
	v_rcp_f32_e32 v29, v29
	v_rcp_f32_e32 v31, v31
	v_rcp_f32_e32 v34, v34
	v_rcp_f32_e32 v32, v32
	v_rcp_f32_e32 v33, v33
	v_rcp_f32_e32 v35, v35
	v_pk_mul_f32 v[18:19], v[18:19], v[130:131] op_sel_hi:[1,0]
	v_pk_mul_f32 v[16:17], v[16:17], v[130:131] op_sel_hi:[1,0]
	v_pk_mul_f32 v[18:19], v[22:23], v[18:19]
	v_pk_mul_f32 v[16:17], v[20:21], v[16:17]
	v_pk_mul_f32 v[20:21], v[18:19], v[28:29]
	v_pk_mul_f32 v[18:19], v[16:17], v[30:31]
	v_pk_mul_f32 v[26:27], v[26:27], v[32:33]
	v_pk_mul_f32 v[24:25], v[24:25], v[34:35]
	v_pk_mul_f32 v[14:15], v[14:15], v[128:129] op_sel_hi:[1,0]
	v_cvt_pk_bf16_f32 v16, v24, v25
	v_cvt_pk_bf16_f32 v17, v26, v27
	v_cvt_pk_bf16_f32 v18, v18, v19
	v_cvt_pk_bf16_f32 v19, v20, v21
	v_mad_i64_i32 v[20:21], s[4:5], v168, s35, v[112:113]
	v_lshl_add_u64 v[20:21], v[20:21], 0, v[114:115]
	v_pk_mul_f32 v[12:13], v[12:13], v[128:129] op_sel_hi:[1,0]
	v_pk_mul_f32 v[10:11], v[10:11], v[128:129] op_sel_hi:[1,0]
	v_pk_mul_f32 v[8:9], v[8:9], v[128:129] op_sel_hi:[1,0]
	v_pk_mul_f32 v[6:7], v[6:7], v[128:129] op_sel_hi:[1,0]
	v_pk_mul_f32 v[4:5], v[4:5], v[128:129] op_sel_hi:[1,0]
	global_store_dwordx4 v[20:21], v[16:19], off
	v_pk_mul_f32 v[8:9], v[12:13], v[8:9]
	v_pk_mul_f32 v[10:11], v[14:15], v[10:11]
	v_pk_mul_f32 v[16:17], v[14:15], s[44:45] op_sel_hi:[1,0]
	v_pk_mul_f32 v[18:19], v[12:13], s[44:45] op_sel_hi:[1,0]
	v_pk_mul_f32 v[12:13], v[6:7], s[44:45] op_sel_hi:[1,0]
	v_pk_mul_f32 v[14:15], v[4:5], s[44:45] op_sel_hi:[1,0]
	v_exp_f32_e32 v12, v12
	v_exp_f32_e32 v14, v14
	v_exp_f32_e32 v13, v13
	v_exp_f32_e32 v15, v15
	v_exp_f32_e32 v18, v18
	v_exp_f32_e32 v16, v16
	v_exp_f32_e32 v17, v17
	v_exp_f32_e32 v19, v19
	v_pk_add_f32 v[12:13], v[12:13], 1.0 op_sel_hi:[1,0]
	v_pk_add_f32 v[14:15], v[14:15], 1.0 op_sel_hi:[1,0]
	v_pk_add_f32 v[16:17], v[16:17], 1.0 op_sel_hi:[1,0]
	v_pk_add_f32 v[18:19], v[18:19], 1.0 op_sel_hi:[1,0]
	v_rcp_f32_e32 v14, v14
	v_rcp_f32_e32 v12, v12
	v_rcp_f32_e32 v13, v13
	v_rcp_f32_e32 v15, v15
	v_rcp_f32_e32 v18, v18
	v_rcp_f32_e32 v16, v16
	v_rcp_f32_e32 v17, v17
	v_rcp_f32_e32 v19, v19
	v_pk_mul_f32 v[2:3], v[2:3], v[128:129] op_sel_hi:[1,0]
	v_pk_mul_f32 v[0:1], v[0:1], v[128:129] op_sel_hi:[1,0]
	v_pk_mul_f32 v[2:3], v[6:7], v[2:3]
	v_pk_mul_f32 v[0:1], v[4:5], v[0:1]
	v_pk_mul_f32 v[4:5], v[2:3], v[12:13]
	v_pk_mul_f32 v[2:3], v[0:1], v[14:15]
	v_pk_mul_f32 v[10:11], v[10:11], v[16:17]
	v_pk_mul_f32 v[8:9], v[8:9], v[18:19]
	s_andn2_b64 vcc, exec, s[2:3]
	v_cvt_pk_bf16_f32 v0, v8, v9
	v_cvt_pk_bf16_f32 v1, v10, v11
	v_cvt_pk_bf16_f32 v2, v2, v3
	v_cvt_pk_bf16_f32 v3, v4, v5
	v_mad_i64_i32 v[4:5], s[4:5], v166, s35, v[112:113]
	v_lshl_add_u64 v[4:5], v[4:5], 0, v[114:115]
	s_mov_b32 s4, s16
	s_mov_b32 s5, s12
	s_mov_b64 s[6:7], s[18:19]
	global_store_dwordx4 v[4:5], v[0:3], off
	s_cbranch_vccnz .LBB0_1429
	s_waitcnt vmcnt(0)
	s_cmpk_gt_u32 s24, 0xff
	s_cbranch_scc1 .LBB0_1440
	s_barrier
